# k76 plus remaining m0-write fillers replaced by ds_reads and 64-byte aligned loop heads
# speedup vs baseline: 1.0064x; 1.0064x over previous
.LBB0_118:
	ds_read_b128 v[128:131], v221
	ds_read_b128 v[132:135], v221 offset:1024
	ds_read_b128 v[136:139], v221 offset:2048
	ds_read_b128 v[140:143], v221 offset:3072
	s_add_u32 s8, s6, 0xfff80080
	s_addc_u32 s9, s7, -1
	s_cmp_eq_u32 s53, 28
	s_cselect_b32 s11, s5, s9
	s_cselect_b32 s10, s33, s8
	s_cselect_b32 s9, s43, s52
	s_cselect_b32 s8, s45, s51

	s_add_i32 m0, s58, 0xc000
	ds_read_b128 v[144:147], v222
	ds_read_b128 v[148:151], v222 offset:1024
	ds_read_b128 v[152:155], v222 offset:2048
	ds_read_b128 v[156:159], v222 offset:3072
	ds_read_b128 v[160:163], v222 offset:4096
	ds_read_b128 v[164:167], v222 offset:5120
	ds_read_b128 v[190:193], v222 offset:6144

	global_load_lds_dwordx4 v182, s[6:7]
	s_add_i32 m0, s58, 0xe000
	ds_read_b128 v[194:197], v222 offset:7168

	global_load_lds_dwordx4 v184, s[6:7]
	s_waitcnt lgkmcnt(8)
	s_barrier
	s_waitcnt lgkmcnt(0)


	v_mfma_f32_16x16x32_bf16 v[124:127], v[128:131], v[144:147], v[124:127]
	v_mfma_f32_16x16x32_bf16 v[116:119], v[136:139], v[144:147], v[116:119]
	v_mfma_f32_16x16x32_bf16 v[108:111], v[128:131], v[152:155], v[108:111]
	v_mfma_f32_16x16x32_bf16 v[100:103], v[136:139], v[152:155], v[100:103]
	v_mfma_f32_16x16x32_bf16 v[92:95], v[128:131], v[160:163], v[92:95]
	v_mfma_f32_16x16x32_bf16 v[84:87], v[136:139], v[160:163], v[84:87]
	v_mfma_f32_16x16x32_bf16 v[76:79], v[128:131], v[190:193], v[76:79]
	v_mfma_f32_16x16x32_bf16 v[68:71], v[136:139], v[190:193], v[68:71]
	v_mfma_f32_16x16x32_bf16 v[124:127], v[132:135], v[148:151], v[124:127]
	v_mfma_f32_16x16x32_bf16 v[116:119], v[140:143], v[148:151], v[116:119]
	v_mfma_f32_16x16x32_bf16 v[108:111], v[132:135], v[156:159], v[108:111]
	v_mfma_f32_16x16x32_bf16 v[100:103], v[140:143], v[156:159], v[100:103]
	v_mfma_f32_16x16x32_bf16 v[92:95], v[132:135], v[164:167], v[92:95]
	v_mfma_f32_16x16x32_bf16 v[84:87], v[140:143], v[164:167], v[84:87]
	v_mfma_f32_16x16x32_bf16 v[76:79], v[132:135], v[194:197], v[76:79]
	v_mfma_f32_16x16x32_bf16 v[68:71], v[140:143], v[194:197], v[68:71]

	s_barrier
	s_add_i32 s54, s81, s57
	s_add_u32 s66, s8, s20
	s_addc_u32 s67, s9, s21
	s_mov_b32 m0, s54
	ds_read_b128 v[198:201], v223
	ds_read_b128 v[202:205], v223 offset:1024
	ds_read_b128 v[206:209], v223 offset:2048

	global_load_lds_dwordx4 v172, s[8:9]
	s_add_i32 m0, s54, 0x2000
	ds_read_b128 v[226:229], v223 offset:3072

	global_load_lds_dwordx4 v174, s[8:9]
	s_barrier
	s_waitcnt lgkmcnt(0)


	v_mfma_f32_16x16x32_bf16 v[120:123], v[198:201], v[144:147], v[120:123]
	v_mfma_f32_16x16x32_bf16 v[112:115], v[206:209], v[144:147], v[112:115]
	v_mfma_f32_16x16x32_bf16 v[104:107], v[198:201], v[152:155], v[104:107]
	v_mfma_f32_16x16x32_bf16 v[96:99], v[206:209], v[152:155], v[96:99]
	v_mfma_f32_16x16x32_bf16 v[88:91], v[198:201], v[160:163], v[88:91]
	v_mfma_f32_16x16x32_bf16 v[80:83], v[206:209], v[160:163], v[80:83]
	v_mfma_f32_16x16x32_bf16 v[72:75], v[198:201], v[190:193], v[72:75]
	v_mfma_f32_16x16x32_bf16 v[64:67], v[206:209], v[190:193], v[64:67]
	v_mfma_f32_16x16x32_bf16 v[120:123], v[202:205], v[148:151], v[120:123]
	v_mfma_f32_16x16x32_bf16 v[112:115], v[226:229], v[148:151], v[112:115]
	v_mfma_f32_16x16x32_bf16 v[104:107], v[202:205], v[156:159], v[104:107]
	v_mfma_f32_16x16x32_bf16 v[96:99], v[226:229], v[156:159], v[96:99]
	v_mfma_f32_16x16x32_bf16 v[88:91], v[202:205], v[164:167], v[88:91]
	v_mfma_f32_16x16x32_bf16 v[80:83], v[226:229], v[164:167], v[80:83]
	v_mfma_f32_16x16x32_bf16 v[72:75], v[202:205], v[194:197], v[72:75]
	v_mfma_f32_16x16x32_bf16 v[64:67], v[226:229], v[194:197], v[64:67]

	s_mov_b32 m0, s58
	s_add_u32 s68, s10, s20
	s_addc_u32 s69, s11, s21
	s_barrier
	ds_read_b128 v[144:147], v222 offset:16384
	ds_read_b128 v[148:151], v222 offset:17408
	ds_read_b128 v[152:155], v222 offset:18432
	ds_read_b128 v[156:159], v222 offset:19456
	ds_read_b128 v[160:163], v222 offset:20480
	ds_read_b128 v[164:167], v222 offset:21504
	ds_read_b128 v[190:193], v222 offset:22528

	global_load_lds_dwordx4 v172, s[10:11]
	s_mov_b32 m0, s59
	ds_read_b128 v[194:197], v222 offset:23552

	global_load_lds_dwordx4 v174, s[10:11]
	s_barrier
	s_waitcnt lgkmcnt(0)


	v_mfma_f32_16x16x32_bf16 v[60:63], v[128:131], v[144:147], v[60:63]
	v_mfma_f32_16x16x32_bf16 v[52:55], v[136:139], v[144:147], v[52:55]
	v_mfma_f32_16x16x32_bf16 v[44:47], v[128:131], v[152:155], v[44:47]
	v_mfma_f32_16x16x32_bf16 v[36:39], v[136:139], v[152:155], v[36:39]
	v_mfma_f32_16x16x32_bf16 v[28:31], v[128:131], v[160:163], v[28:31]
	v_mfma_f32_16x16x32_bf16 v[20:23], v[136:139], v[160:163], v[20:23]
	v_mfma_f32_16x16x32_bf16 v[12:15], v[128:131], v[190:193], v[12:15]
	v_mfma_f32_16x16x32_bf16 v[4:7], v[136:139], v[190:193], v[4:7]
	v_mfma_f32_16x16x32_bf16 v[60:63], v[132:135], v[148:151], v[60:63]
	v_mfma_f32_16x16x32_bf16 v[52:55], v[140:143], v[148:151], v[52:55]
	v_mfma_f32_16x16x32_bf16 v[44:47], v[132:135], v[156:159], v[44:47]
	v_mfma_f32_16x16x32_bf16 v[36:39], v[140:143], v[156:159], v[36:39]
	v_mfma_f32_16x16x32_bf16 v[28:31], v[132:135], v[164:167], v[28:31]
	v_mfma_f32_16x16x32_bf16 v[20:23], v[140:143], v[164:167], v[20:23]
	v_mfma_f32_16x16x32_bf16 v[12:15], v[132:135], v[194:197], v[12:15]
	v_mfma_f32_16x16x32_bf16 v[4:7], v[140:143], v[194:197], v[4:7]

	s_barrier
	s_add_u32 s54, s8, 0x80000
	s_addc_u32 s55, s9, 0
	s_add_i32 vcc_lo, s30, s57
	s_mov_b32 m0, vcc_lo
	s_nop 0

	global_load_lds_dwordx4 v172, s[54:55]
	s_add_i32 m0, vcc_lo, 0x2000
	s_nop 0

	global_load_lds_dwordx4 v174, s[54:55]
	s_waitcnt vmcnt(6)
	s_barrier

	v_mfma_f32_16x16x32_bf16 v[56:59], v[198:201], v[144:147], v[56:59]
	v_mfma_f32_16x16x32_bf16 v[48:51], v[206:209], v[144:147], v[48:51]
	v_mfma_f32_16x16x32_bf16 v[40:43], v[198:201], v[152:155], v[40:43]
	v_mfma_f32_16x16x32_bf16 v[32:35], v[206:209], v[152:155], v[32:35]
	v_mfma_f32_16x16x32_bf16 v[24:27], v[198:201], v[160:163], v[24:27]
	v_mfma_f32_16x16x32_bf16 v[16:19], v[206:209], v[160:163], v[16:19]
	v_mfma_f32_16x16x32_bf16 v[8:11], v[198:201], v[190:193], v[8:11]
	v_mfma_f32_16x16x32_bf16 v[0:3], v[206:209], v[190:193], v[0:3]
	v_mfma_f32_16x16x32_bf16 v[56:59], v[202:205], v[148:151], v[56:59]
	v_mfma_f32_16x16x32_bf16 v[48:51], v[226:229], v[148:151], v[48:51]
	v_mfma_f32_16x16x32_bf16 v[40:43], v[202:205], v[156:159], v[40:43]
	v_mfma_f32_16x16x32_bf16 v[32:35], v[226:229], v[156:159], v[32:35]
	v_mfma_f32_16x16x32_bf16 v[24:27], v[202:205], v[164:167], v[24:27]
	v_mfma_f32_16x16x32_bf16 v[16:19], v[226:229], v[164:167], v[16:19]
	v_mfma_f32_16x16x32_bf16 v[8:11], v[202:205], v[194:197], v[8:11]
	v_mfma_f32_16x16x32_bf16 v[0:3], v[226:229], v[194:197], v[0:3]

	s_add_i32 s54, 0, 0x18000

	s_barrier
	ds_read_b128 v[128:131], v221 offset:32768
	ds_read_b128 v[132:135], v221 offset:33792
	ds_read_b128 v[136:139], v221 offset:34816
	ds_read_b128 v[140:143], v221 offset:35840
	s_add_u32 s10, s10, 0x80000
	s_addc_u32 s11, s11, 0
	s_mov_b32 m0, s2

	ds_read_b128 v[144:147], v222 offset:32768
	ds_read_b128 v[148:151], v222 offset:33792
	ds_read_b128 v[152:155], v222 offset:34816
	ds_read_b128 v[156:159], v222 offset:35840
	ds_read_b128 v[160:163], v222 offset:36864
	ds_read_b128 v[164:167], v222 offset:37888
	ds_read_b128 v[190:193], v222 offset:38912

	global_load_lds_dwordx4 v172, s[10:11]
	s_mov_b32 m0, s3
	ds_read_b128 v[194:197], v222 offset:39936

	global_load_lds_dwordx4 v174, s[10:11]
	s_waitcnt lgkmcnt(8)
	s_barrier
	s_waitcnt lgkmcnt(0)


	v_mfma_f32_16x16x32_bf16 v[124:127], v[128:131], v[144:147], v[124:127]
	v_mfma_f32_16x16x32_bf16 v[116:119], v[136:139], v[144:147], v[116:119]
	v_mfma_f32_16x16x32_bf16 v[108:111], v[128:131], v[152:155], v[108:111]
	v_mfma_f32_16x16x32_bf16 v[100:103], v[136:139], v[152:155], v[100:103]
	v_mfma_f32_16x16x32_bf16 v[92:95], v[128:131], v[160:163], v[92:95]
	v_mfma_f32_16x16x32_bf16 v[84:87], v[136:139], v[160:163], v[84:87]
	v_mfma_f32_16x16x32_bf16 v[76:79], v[128:131], v[190:193], v[76:79]
	v_mfma_f32_16x16x32_bf16 v[68:71], v[136:139], v[190:193], v[68:71]
	v_mfma_f32_16x16x32_bf16 v[124:127], v[132:135], v[148:151], v[124:127]
	v_mfma_f32_16x16x32_bf16 v[116:119], v[140:143], v[148:151], v[116:119]
	v_mfma_f32_16x16x32_bf16 v[108:111], v[132:135], v[156:159], v[108:111]
	v_mfma_f32_16x16x32_bf16 v[100:103], v[140:143], v[156:159], v[100:103]
	v_mfma_f32_16x16x32_bf16 v[92:95], v[132:135], v[164:167], v[92:95]
	v_mfma_f32_16x16x32_bf16 v[84:87], v[140:143], v[164:167], v[84:87]
	v_mfma_f32_16x16x32_bf16 v[76:79], v[132:135], v[194:197], v[76:79]
	v_mfma_f32_16x16x32_bf16 v[68:71], v[140:143], v[194:197], v[68:71]

	s_barrier
	s_add_i32 s10, 0, 0x1c000
	s_add_i32 s11, s54, s57


	s_mov_b32 m0, s11
	ds_read_b128 v[198:201], v223 offset:32768
	ds_read_b128 v[202:205], v223 offset:33792
	ds_read_b128 v[206:209], v223 offset:34816

	global_load_lds_dwordx4 v172, s[66:67]
	s_add_i32 m0, s11, 0x2000
	ds_read_b128 v[226:229], v223 offset:35840

	global_load_lds_dwordx4 v174, s[66:67]
	s_barrier
	s_waitcnt lgkmcnt(0)


	v_mfma_f32_16x16x32_bf16 v[120:123], v[198:201], v[144:147], v[120:123]
	v_mfma_f32_16x16x32_bf16 v[112:115], v[206:209], v[144:147], v[112:115]
	v_mfma_f32_16x16x32_bf16 v[104:107], v[198:201], v[152:155], v[104:107]
	v_mfma_f32_16x16x32_bf16 v[96:99], v[206:209], v[152:155], v[96:99]
	v_mfma_f32_16x16x32_bf16 v[88:91], v[198:201], v[160:163], v[88:91]
	v_mfma_f32_16x16x32_bf16 v[80:83], v[206:209], v[160:163], v[80:83]
	v_mfma_f32_16x16x32_bf16 v[72:75], v[198:201], v[190:193], v[72:75]
	v_mfma_f32_16x16x32_bf16 v[64:67], v[206:209], v[190:193], v[64:67]
	v_mfma_f32_16x16x32_bf16 v[120:123], v[202:205], v[148:151], v[120:123]
	v_mfma_f32_16x16x32_bf16 v[112:115], v[226:229], v[148:151], v[112:115]
	v_mfma_f32_16x16x32_bf16 v[104:107], v[202:205], v[156:159], v[104:107]
	v_mfma_f32_16x16x32_bf16 v[96:99], v[226:229], v[156:159], v[96:99]
	v_mfma_f32_16x16x32_bf16 v[88:91], v[202:205], v[164:167], v[88:91]
	v_mfma_f32_16x16x32_bf16 v[80:83], v[226:229], v[164:167], v[80:83]
	v_mfma_f32_16x16x32_bf16 v[72:75], v[202:205], v[194:197], v[72:75]
	v_mfma_f32_16x16x32_bf16 v[64:67], v[226:229], v[194:197], v[64:67]

	s_mov_b32 m0, s96

	s_barrier
	ds_read_b128 v[144:147], v222 offset:49152
	ds_read_b128 v[148:151], v222 offset:50176
	ds_read_b128 v[152:155], v222 offset:51200
	ds_read_b128 v[156:159], v222 offset:52224
	ds_read_b128 v[160:163], v222 offset:53248
	ds_read_b128 v[164:167], v222 offset:54272
	ds_read_b128 v[190:193], v222 offset:55296

	global_load_lds_dwordx4 v172, s[68:69]
	s_mov_b32 m0, s97
	ds_read_b128 v[194:197], v222 offset:56320

	global_load_lds_dwordx4 v174, s[68:69]
	s_barrier
	s_waitcnt lgkmcnt(0)


	v_mfma_f32_16x16x32_bf16 v[60:63], v[128:131], v[144:147], v[60:63]
	v_mfma_f32_16x16x32_bf16 v[52:55], v[136:139], v[144:147], v[52:55]
	v_mfma_f32_16x16x32_bf16 v[44:47], v[128:131], v[152:155], v[44:47]
	v_mfma_f32_16x16x32_bf16 v[36:39], v[136:139], v[152:155], v[36:39]
	v_mfma_f32_16x16x32_bf16 v[28:31], v[128:131], v[160:163], v[28:31]
	v_mfma_f32_16x16x32_bf16 v[20:23], v[136:139], v[160:163], v[20:23]
	v_mfma_f32_16x16x32_bf16 v[12:15], v[128:131], v[190:193], v[12:15]
	v_mfma_f32_16x16x32_bf16 v[4:7], v[136:139], v[190:193], v[4:7]
	v_mfma_f32_16x16x32_bf16 v[60:63], v[132:135], v[148:151], v[60:63]
	v_mfma_f32_16x16x32_bf16 v[52:55], v[140:143], v[148:151], v[52:55]
	v_mfma_f32_16x16x32_bf16 v[44:47], v[132:135], v[156:159], v[44:47]
	v_mfma_f32_16x16x32_bf16 v[36:39], v[140:143], v[156:159], v[36:39]
	v_mfma_f32_16x16x32_bf16 v[28:31], v[132:135], v[164:167], v[28:31]
	v_mfma_f32_16x16x32_bf16 v[20:23], v[140:143], v[164:167], v[20:23]
	v_mfma_f32_16x16x32_bf16 v[12:15], v[132:135], v[194:197], v[12:15]
	v_mfma_f32_16x16x32_bf16 v[4:7], v[140:143], v[194:197], v[4:7]

	s_barrier
	s_add_u32 s8, s8, 0x80080
	s_addc_u32 s9, s9, 0
	s_add_i32 s10, s10, s57
	s_mov_b32 m0, s10
	s_add_i32 s53, s53, 2

	global_load_lds_dwordx4 v172, s[8:9]
	s_add_i32 m0, s10, 0x2000
	s_add_u32 s6, s6, 0x100
	s_addc_u32 s7, s7, 0

	global_load_lds_dwordx4 v174, s[8:9]
	s_add_u32 s51, s51, 0x100
	s_addc_u32 s52, s52, 0
	s_waitcnt vmcnt(6)
	s_barrier

	v_mfma_f32_16x16x32_bf16 v[56:59], v[198:201], v[144:147], v[56:59]
	v_mfma_f32_16x16x32_bf16 v[48:51], v[206:209], v[144:147], v[48:51]
	v_mfma_f32_16x16x32_bf16 v[40:43], v[198:201], v[152:155], v[40:43]
	v_mfma_f32_16x16x32_bf16 v[32:35], v[206:209], v[152:155], v[32:35]
	v_mfma_f32_16x16x32_bf16 v[24:27], v[198:201], v[160:163], v[24:27]
	v_mfma_f32_16x16x32_bf16 v[16:19], v[206:209], v[160:163], v[16:19]
	v_mfma_f32_16x16x32_bf16 v[8:11], v[198:201], v[190:193], v[8:11]
	v_mfma_f32_16x16x32_bf16 v[0:3], v[206:209], v[190:193], v[0:3]
	v_mfma_f32_16x16x32_bf16 v[56:59], v[202:205], v[148:151], v[56:59]
	v_mfma_f32_16x16x32_bf16 v[48:51], v[226:229], v[148:151], v[48:51]
	v_mfma_f32_16x16x32_bf16 v[40:43], v[202:205], v[156:159], v[40:43]
	v_mfma_f32_16x16x32_bf16 v[32:35], v[226:229], v[156:159], v[32:35]
	v_mfma_f32_16x16x32_bf16 v[24:27], v[202:205], v[164:167], v[24:27]
	v_mfma_f32_16x16x32_bf16 v[16:19], v[226:229], v[164:167], v[16:19]
	v_mfma_f32_16x16x32_bf16 v[8:11], v[202:205], v[194:197], v[8:11]
	v_mfma_f32_16x16x32_bf16 v[0:3], v[226:229], v[194:197], v[0:3]


	s_cmp_gt_u32 s53, 29
	s_barrier
	s_cbranch_scc0 .LBB0_118
	v_mov_b32_e32 v142, v210
	v_mov_b32_e32 v143, v169
	s_lshl_b32 s33, s4, 8
	s_add_i32 s33, s33, s34
	v_lshl_add_u32 v133, v142, 4, v143
	v_ashrrev_i32_e32 v198, 2, v133
	v_and_b32_e32 v192, 3, v143
	v_and_b32_e32 v128, -4, v133
	s_cmp_gt_i32 s4, 30
	v_lshl_add_u32 v226, v192, 6, v128
	v_add_u32_e32 v190, s33, v198
	s_cselect_b64 s[52:53], -1, 0
	s_cmp_gt_i32 s50, 8
	s_mov_b64 s[4:5], -1
	s_cbranch_scc0 .LBB0_419
	s_cmp_lg_u32 s50, 9
	s_cbranch_scc0 .LBB0_225
	s_cmp_gt_u32 s50, 25
	s_cbranch_scc0 .LBB0_127
	v_mul_f32_e32 v130, 0xbfb8aa3b, v120
	v_mul_f32_e32 v131, 0xbfb8aa3b, v121
	v_mul_f32_e32 v132, 0xbfb8aa3b, v122
	v_mul_f32_e32 v134, 0xbfb8aa3b, v123
	v_mul_f32_e32 v135, 0xbfb8aa3b, v112
	v_mul_f32_e32 v136, 0xbfb8aa3b, v113
	v_mul_f32_e32 v137, 0xbfb8aa3b, v114
	v_mul_f32_e32 v138, 0xbfb8aa3b, v115
	v_mul_f32_e32 v139, 0xbfb8aa3b, v104
	v_mul_f32_e32 v140, 0xbfb8aa3b, v105
	v_mul_f32_e32 v141, 0xbfb8aa3b, v106
	v_mul_f32_e32 v144, 0xbfb8aa3b, v107
	v_mul_f32_e32 v145, 0xbfb8aa3b, v96
	v_mul_f32_e32 v146, 0xbfb8aa3b, v97
	v_mul_f32_e32 v147, 0xbfb8aa3b, v98
	v_mul_f32_e32 v148, 0xbfb8aa3b, v99
	v_mul_f32_e32 v149, 0xbfb8aa3b, v88
	v_mul_f32_e32 v150, 0xbfb8aa3b, v89
	v_mul_f32_e32 v151, 0xbfb8aa3b, v90
	v_mul_f32_e32 v152, 0xbfb8aa3b, v91
	v_mul_f32_e32 v153, 0xbfb8aa3b, v80
	v_mul_f32_e32 v154, 0xbfb8aa3b, v81
	v_mul_f32_e32 v155, 0xbfb8aa3b, v82
	v_mul_f32_e32 v180, 0xbfb8aa3b, v83
	v_mul_f32_e32 v206, 0xbfb8aa3b, v72
	v_mul_f32_e32 v207, 0xbfb8aa3b, v73
	v_mul_f32_e32 v208, 0xbfb8aa3b, v74
	v_mul_f32_e32 v209, 0xbfb8aa3b, v75
	v_mul_f32_e32 v227, 0xbfb8aa3b, v64
	v_mul_f32_e32 v228, 0xbfb8aa3b, v65
	v_mul_f32_e32 v229, 0xbfb8aa3b, v66
	v_mul_f32_e32 v230, 0xbfb8aa3b, v67
	v_exp_f32_e32 v205, v130
	v_exp_f32_e32 v204, v131
	v_exp_f32_e32 v203, v132
	v_exp_f32_e32 v202, v134
	v_exp_f32_e32 v200, v135
	v_exp_f32_e32 v199, v136
	v_exp_f32_e32 v197, v137
	v_exp_f32_e32 v196, v138
	v_exp_f32_e32 v195, v139
	v_exp_f32_e32 v194, v140
	v_exp_f32_e32 v193, v141
	v_exp_f32_e32 v167, v144
	v_exp_f32_e32 v166, v145
	v_exp_f32_e32 v165, v146
	v_exp_f32_e32 v164, v147
	v_exp_f32_e32 v163, v148
	v_exp_f32_e32 v162, v149
	v_exp_f32_e32 v161, v150
	v_exp_f32_e32 v160, v151
	v_exp_f32_e32 v159, v152
	v_exp_f32_e32 v158, v153
	v_exp_f32_e32 v157, v154
	v_exp_f32_e32 v156, v155
	v_exp_f32_e32 v155, v180
	v_exp_f32_e32 v154, v206
	v_exp_f32_e32 v153, v207
	v_exp_f32_e32 v152, v208
	v_exp_f32_e32 v151, v209
	v_exp_f32_e32 v150, v227
	v_exp_f32_e32 v149, v228
	v_exp_f32_e32 v148, v229
	v_exp_f32_e32 v147, v230
	v_ashrrev_i32_e32 v191, 31, v190
	s_cmp_lt_u32 s50, 42
	v_lshlrev_b32_e32 v201, 2, v192
	v_lshlrev_b64 v[128:129], 12, v[190:191]
	v_mul_f32_e32 v146, 0xbfb8aa3b, v56
	v_mul_f32_e32 v145, 0xbfb8aa3b, v57
	v_mul_f32_e32 v144, 0xbfb8aa3b, v58
	v_mul_f32_e32 v141, 0xbfb8aa3b, v59
	v_mul_f32_e32 v140, 0xbfb8aa3b, v48
	v_mul_f32_e32 v139, 0xbfb8aa3b, v49
	v_mul_f32_e32 v138, 0xbfb8aa3b, v50
	v_mul_f32_e32 v137, 0xbfb8aa3b, v51
	v_mul_f32_e32 v136, 0xbfb8aa3b, v40
	v_mul_f32_e32 v135, 0xbfb8aa3b, v41
	v_mul_f32_e32 v134, 0xbfb8aa3b, v42
	v_mul_f32_e32 v132, 0xbfb8aa3b, v43
	s_cbranch_scc1 .LBB0_124
	v_mul_f32_e32 v130, 0xbfb8aa3b, v124
	v_mul_f32_e32 v131, 0xbfb8aa3b, v125
	v_mul_f32_e32 v206, 0xbfb8aa3b, v126
	v_mul_f32_e32 v207, 0xbfb8aa3b, v127
	v_exp_f32_e32 v130, v130
	v_exp_f32_e32 v131, v131
	v_exp_f32_e32 v206, v206
	v_exp_f32_e32 v207, v207
	v_add_f32_e32 v130, 1.0, v130
	v_add_f32_e32 v131, 1.0, v131
	v_add_f32_e32 v206, 1.0, v206
	v_add_f32_e32 v207, 1.0, v207
	v_rcp_f32_e32 v130, v130
	v_rcp_f32_e32 v131, v131
	v_rcp_f32_e32 v206, v206
	v_rcp_f32_e32 v207, v207
	s_lshl_b32 s4, s50, 8
	v_cvt_pk_bf16_f32 v130, v130, v131
	s_add_i32 s4, s28, s4
	v_cvt_pk_bf16_f32 v131, v206, v207
	ds_bpermute_b32 v206, v226, v130
	ds_bpermute_b32 v207, v226, v131
	v_or_b32_e32 v180, s4, v201
	v_lshl_add_u64 v[130:131], s[40:41], 0, v[128:129]
	v_lshlrev_b64 v[208:209], 1, v[180:181]
	v_lshl_add_u64 v[130:131], v[130:131], 0, v[208:209]
	s_waitcnt lgkmcnt(0)
	global_store_dwordx2 v[130:131], v[206:207], off
	v_mul_f32_e32 v180, 0xbfb8aa3b, v116
	v_mul_f32_e32 v206, 0xbfb8aa3b, v117
	v_mul_f32_e32 v207, 0xbfb8aa3b, v118
	v_mul_f32_e32 v208, 0xbfb8aa3b, v119
	v_exp_f32_e32 v180, v180
	v_exp_f32_e32 v206, v206
	v_exp_f32_e32 v207, v207
	v_exp_f32_e32 v208, v208
	v_add_f32_e32 v180, 1.0, v180
	v_add_f32_e32 v206, 1.0, v206
	v_add_f32_e32 v207, 1.0, v207
	v_add_f32_e32 v208, 1.0, v208
	v_rcp_f32_e32 v180, v180
	v_rcp_f32_e32 v206, v206
	v_rcp_f32_e32 v207, v207
	v_rcp_f32_e32 v208, v208
	s_mov_b64 s[4:5], 0x10000
	v_cvt_pk_bf16_f32 v180, v180, v206
	ds_bpermute_b32 v206, v226, v180
	v_cvt_pk_bf16_f32 v207, v207, v208
	ds_bpermute_b32 v207, v226, v207
	v_add_f32_e32 v180, 1.0, v205
	v_add_f32_e32 v208, 1.0, v202
	v_rcp_f32_e32 v180, v180
	v_rcp_f32_e32 v208, v208
	s_waitcnt lgkmcnt(0)
	global_store_dwordx2 v[130:131], v[206:207], off offset:32
	v_add_f32_e32 v206, 1.0, v204
	v_add_f32_e32 v207, 1.0, v203
	v_rcp_f32_e32 v206, v206
	v_rcp_f32_e32 v207, v207
	v_mul_f32_e32 v227, 0xbfb8aa3b, v103
	v_exp_f32_e32 v227, v227
	v_cvt_pk_bf16_f32 v180, v180, v206
	v_cvt_pk_bf16_f32 v207, v207, v208
	ds_bpermute_b32 v206, v226, v180
	ds_bpermute_b32 v207, v226, v207
	v_add_f32_e32 v180, 1.0, v200
	v_add_f32_e32 v208, 1.0, v196
	v_rcp_f32_e32 v180, v180
	v_rcp_f32_e32 v208, v208
	s_waitcnt lgkmcnt(0)
	global_store_dwordx2 v[130:131], v[206:207], off offset:256
	v_add_f32_e32 v206, 1.0, v199
	v_add_f32_e32 v207, 1.0, v197
	v_rcp_f32_e32 v206, v206
	v_rcp_f32_e32 v207, v207
	v_add_f32_e32 v227, 1.0, v227
	v_rcp_f32_e32 v227, v227
	v_cvt_pk_bf16_f32 v180, v180, v206
	v_cvt_pk_bf16_f32 v207, v207, v208
	ds_bpermute_b32 v206, v226, v180
	ds_bpermute_b32 v207, v226, v207
	v_mul_f32_e32 v180, 0xbfb8aa3b, v108
	v_mul_f32_e32 v208, 0xbfb8aa3b, v111
	v_exp_f32_e32 v180, v180
	v_exp_f32_e32 v208, v208
	s_waitcnt lgkmcnt(0)
	global_store_dwordx2 v[130:131], v[206:207], off offset:288
	v_mul_f32_e32 v206, 0xbfb8aa3b, v109
	v_mul_f32_e32 v207, 0xbfb8aa3b, v110
	v_exp_f32_e32 v206, v206
	v_exp_f32_e32 v207, v207
	v_add_f32_e32 v180, 1.0, v180
	v_add_f32_e32 v208, 1.0, v208
	v_add_f32_e32 v206, 1.0, v206
	v_add_f32_e32 v207, 1.0, v207
	v_rcp_f32_e32 v180, v180
	v_rcp_f32_e32 v206, v206
	v_rcp_f32_e32 v207, v207
	v_rcp_f32_e32 v208, v208
	v_cvt_pk_bf16_f32 v180, v180, v206
	ds_bpermute_b32 v206, v226, v180
	v_cvt_pk_bf16_f32 v207, v207, v208
	ds_bpermute_b32 v207, v226, v207
	v_lshl_add_u64 v[208:209], v[130:131], 0, s[4:5]
	s_mov_b32 s4, 0x10000
	v_add_co_u32_e32 v228, vcc, s4, v130
	v_mul_f32_e32 v180, 0xbfb8aa3b, v100
	s_nop 0
	v_addc_co_u32_e32 v229, vcc, 0, v131, vcc
	s_waitcnt lgkmcnt(0)
	global_store_dwordx2 v[228:229], v[206:207], off
	v_mul_f32_e32 v206, 0xbfb8aa3b, v101
	v_mul_f32_e32 v207, 0xbfb8aa3b, v102
	v_exp_f32_e32 v180, v180
	v_exp_f32_e32 v206, v206
	v_exp_f32_e32 v207, v207
	s_mov_b64 s[4:5], 0x20000
	v_add_f32_e32 v180, 1.0, v180
	v_add_f32_e32 v206, 1.0, v206
	v_add_f32_e32 v207, 1.0, v207
	v_rcp_f32_e32 v180, v180
	v_rcp_f32_e32 v206, v206
	v_rcp_f32_e32 v207, v207
	v_cvt_pk_bf16_f32 v180, v180, v206
	v_cvt_pk_bf16_f32 v207, v207, v227
	ds_bpermute_b32 v206, v226, v180
	ds_bpermute_b32 v207, v226, v207
	v_add_f32_e32 v180, 1.0, v195
	v_add_f32_e32 v227, 1.0, v167
	v_rcp_f32_e32 v180, v180
	v_rcp_f32_e32 v227, v227
	s_waitcnt lgkmcnt(0)
	global_store_dwordx2 v[208:209], v[206:207], off offset:32
	v_add_f32_e32 v206, 1.0, v194
	v_add_f32_e32 v207, 1.0, v193
	v_rcp_f32_e32 v206, v206
	v_rcp_f32_e32 v207, v207
	v_cvt_pk_bf16_f32 v180, v180, v206
	v_cvt_pk_bf16_f32 v207, v207, v227
	ds_bpermute_b32 v206, v226, v180
	ds_bpermute_b32 v207, v226, v207
	v_add_f32_e32 v180, 1.0, v166
	v_add_f32_e32 v227, 1.0, v163
	v_rcp_f32_e32 v180, v180
	v_rcp_f32_e32 v227, v227
	s_waitcnt lgkmcnt(0)
	global_store_dwordx2 v[208:209], v[206:207], off offset:256
	v_add_f32_e32 v206, 1.0, v165
	v_add_f32_e32 v207, 1.0, v164
	v_rcp_f32_e32 v206, v206
	v_rcp_f32_e32 v207, v207
	v_cvt_pk_bf16_f32 v180, v180, v206
	v_cvt_pk_bf16_f32 v207, v207, v227
	ds_bpermute_b32 v206, v226, v180
	ds_bpermute_b32 v207, v226, v207
	v_mul_f32_e32 v180, 0xbfb8aa3b, v92
	v_exp_f32_e32 v180, v180
	v_mul_f32_e32 v227, 0xbfb8aa3b, v87
	v_exp_f32_e32 v227, v227
	s_waitcnt lgkmcnt(0)
	global_store_dwordx2 v[208:209], v[206:207], off offset:288
	v_mul_f32_e32 v206, 0xbfb8aa3b, v93
	v_mul_f32_e32 v207, 0xbfb8aa3b, v94
	v_mul_f32_e32 v208, 0xbfb8aa3b, v95
	v_exp_f32_e32 v206, v206
	v_exp_f32_e32 v207, v207
	v_exp_f32_e32 v208, v208
	v_add_f32_e32 v180, 1.0, v180
	v_add_f32_e32 v206, 1.0, v206
	v_add_f32_e32 v207, 1.0, v207
	v_add_f32_e32 v208, 1.0, v208
	v_rcp_f32_e32 v180, v180
	v_rcp_f32_e32 v206, v206
	v_rcp_f32_e32 v207, v207
	v_rcp_f32_e32 v208, v208
	v_add_f32_e32 v227, 1.0, v227
	v_cvt_pk_bf16_f32 v180, v180, v206
	ds_bpermute_b32 v206, v226, v180
	v_cvt_pk_bf16_f32 v207, v207, v208
	ds_bpermute_b32 v207, v226, v207
	v_lshl_add_u64 v[208:209], v[130:131], 0, s[4:5]
	s_mov_b32 s4, 0x20000
	v_add_co_u32_e32 v228, vcc, s4, v130
	v_mul_f32_e32 v180, 0xbfb8aa3b, v84
	s_nop 0
	v_addc_co_u32_e32 v229, vcc, 0, v131, vcc
	s_waitcnt lgkmcnt(0)
	global_store_dwordx2 v[228:229], v[206:207], off
	v_mul_f32_e32 v206, 0xbfb8aa3b, v85
	v_mul_f32_e32 v207, 0xbfb8aa3b, v86
	v_exp_f32_e32 v180, v180
	v_exp_f32_e32 v206, v206
	v_exp_f32_e32 v207, v207
	v_rcp_f32_e32 v227, v227
	v_add_f32_e32 v180, 1.0, v180
	v_add_f32_e32 v206, 1.0, v206
	v_add_f32_e32 v207, 1.0, v207
	v_rcp_f32_e32 v180, v180
	v_rcp_f32_e32 v206, v206
	v_rcp_f32_e32 v207, v207
	s_mov_b64 s[4:5], 0x30000
	v_cvt_pk_bf16_f32 v180, v180, v206
	v_cvt_pk_bf16_f32 v207, v207, v227
	ds_bpermute_b32 v206, v226, v180
	ds_bpermute_b32 v207, v226, v207
	v_add_f32_e32 v180, 1.0, v162
	v_add_f32_e32 v227, 1.0, v159
	v_rcp_f32_e32 v180, v180
	v_rcp_f32_e32 v227, v227
	s_waitcnt lgkmcnt(0)
	global_store_dwordx2 v[208:209], v[206:207], off offset:32
	v_add_f32_e32 v206, 1.0, v161
	v_add_f32_e32 v207, 1.0, v160
	v_rcp_f32_e32 v206, v206
	v_rcp_f32_e32 v207, v207
	v_cvt_pk_bf16_f32 v180, v180, v206
	v_cvt_pk_bf16_f32 v207, v207, v227
	ds_bpermute_b32 v206, v226, v180
	ds_bpermute_b32 v207, v226, v207
	v_add_f32_e32 v180, 1.0, v158
	v_add_f32_e32 v227, 1.0, v155
	v_rcp_f32_e32 v180, v180
	v_rcp_f32_e32 v227, v227
	s_waitcnt lgkmcnt(0)
	global_store_dwordx2 v[208:209], v[206:207], off offset:256
	v_add_f32_e32 v206, 1.0, v157
	v_add_f32_e32 v207, 1.0, v156
	v_rcp_f32_e32 v206, v206
	v_rcp_f32_e32 v207, v207
	v_cvt_pk_bf16_f32 v180, v180, v206
	v_cvt_pk_bf16_f32 v207, v207, v227
	ds_bpermute_b32 v206, v226, v180
	ds_bpermute_b32 v207, v226, v207
	v_mul_f32_e32 v180, 0xbfb8aa3b, v76
	v_exp_f32_e32 v180, v180
	v_mul_f32_e32 v227, 0xbfb8aa3b, v71
	v_exp_f32_e32 v227, v227
	s_waitcnt lgkmcnt(0)
	global_store_dwordx2 v[208:209], v[206:207], off offset:288
	v_mul_f32_e32 v206, 0xbfb8aa3b, v77
	v_mul_f32_e32 v207, 0xbfb8aa3b, v78
	v_mul_f32_e32 v208, 0xbfb8aa3b, v79
	v_exp_f32_e32 v206, v206
	v_exp_f32_e32 v207, v207
	v_exp_f32_e32 v208, v208
	v_add_f32_e32 v180, 1.0, v180
	v_add_f32_e32 v206, 1.0, v206
	v_add_f32_e32 v207, 1.0, v207
	v_add_f32_e32 v208, 1.0, v208
	v_rcp_f32_e32 v180, v180
	v_rcp_f32_e32 v206, v206
	v_rcp_f32_e32 v207, v207
	v_rcp_f32_e32 v208, v208
	v_add_f32_e32 v227, 1.0, v227
	v_cvt_pk_bf16_f32 v180, v180, v206
	ds_bpermute_b32 v206, v226, v180
	v_cvt_pk_bf16_f32 v207, v207, v208
	ds_bpermute_b32 v207, v226, v207
	v_lshl_add_u64 v[208:209], v[130:131], 0, s[4:5]
	s_mov_b32 s4, 0x30000
	v_add_co_u32_e32 v228, vcc, s4, v130
	v_mul_f32_e32 v180, 0xbfb8aa3b, v68
	s_nop 0
	v_addc_co_u32_e32 v229, vcc, 0, v131, vcc
	s_waitcnt lgkmcnt(0)
	global_store_dwordx2 v[228:229], v[206:207], off
	v_mul_f32_e32 v206, 0xbfb8aa3b, v69
	v_mul_f32_e32 v207, 0xbfb8aa3b, v70
	v_exp_f32_e32 v180, v180
	v_exp_f32_e32 v206, v206
	v_exp_f32_e32 v207, v207
	v_rcp_f32_e32 v227, v227
	v_add_f32_e32 v180, 1.0, v180
	v_add_f32_e32 v206, 1.0, v206
	v_add_f32_e32 v207, 1.0, v207
	v_rcp_f32_e32 v180, v180
	v_rcp_f32_e32 v206, v206
	v_rcp_f32_e32 v207, v207
	s_mov_b64 s[4:5], 0x80000
	v_cvt_pk_bf16_f32 v180, v180, v206
	v_cvt_pk_bf16_f32 v207, v207, v227
	ds_bpermute_b32 v206, v226, v180
	ds_bpermute_b32 v207, v226, v207
	v_add_f32_e32 v180, 1.0, v154
	v_add_f32_e32 v227, 1.0, v151
	v_rcp_f32_e32 v180, v180
	v_rcp_f32_e32 v227, v227
	s_waitcnt lgkmcnt(0)
	global_store_dwordx2 v[208:209], v[206:207], off offset:32
	v_add_f32_e32 v206, 1.0, v153
	v_add_f32_e32 v207, 1.0, v152
	v_rcp_f32_e32 v206, v206
	v_rcp_f32_e32 v207, v207
	v_cvt_pk_bf16_f32 v180, v180, v206
	v_cvt_pk_bf16_f32 v207, v207, v227
	ds_bpermute_b32 v206, v226, v180
	ds_bpermute_b32 v207, v226, v207
	v_add_f32_e32 v180, 1.0, v150
	v_add_f32_e32 v227, 1.0, v147
	v_rcp_f32_e32 v180, v180
	v_rcp_f32_e32 v227, v227
	s_waitcnt lgkmcnt(0)
	global_store_dwordx2 v[208:209], v[206:207], off offset:256
	v_add_f32_e32 v206, 1.0, v149
	v_add_f32_e32 v207, 1.0, v148
	v_rcp_f32_e32 v206, v206
	v_rcp_f32_e32 v207, v207
	v_cvt_pk_bf16_f32 v180, v180, v206
	v_cvt_pk_bf16_f32 v207, v207, v227
	ds_bpermute_b32 v206, v226, v180
	ds_bpermute_b32 v207, v226, v207
	v_mul_f32_e32 v180, 0xbfb8aa3b, v60
	v_exp_f32_e32 v180, v180
	v_mul_f32_e32 v227, 0xbfb8aa3b, v55
	v_exp_f32_e32 v227, v227
	s_waitcnt lgkmcnt(0)
	global_store_dwordx2 v[208:209], v[206:207], off offset:288
	v_mul_f32_e32 v206, 0xbfb8aa3b, v61
	v_mul_f32_e32 v207, 0xbfb8aa3b, v62
	v_mul_f32_e32 v208, 0xbfb8aa3b, v63
	v_exp_f32_e32 v206, v206
	v_exp_f32_e32 v207, v207
	v_exp_f32_e32 v208, v208
	v_add_f32_e32 v180, 1.0, v180
	v_add_f32_e32 v206, 1.0, v206
	v_add_f32_e32 v207, 1.0, v207
	v_add_f32_e32 v208, 1.0, v208
	v_rcp_f32_e32 v180, v180
	v_rcp_f32_e32 v206, v206
	v_rcp_f32_e32 v207, v207
	v_rcp_f32_e32 v208, v208
	v_add_f32_e32 v227, 1.0, v227
	v_cvt_pk_bf16_f32 v180, v180, v206
	ds_bpermute_b32 v206, v226, v180
	v_cvt_pk_bf16_f32 v207, v207, v208
	ds_bpermute_b32 v207, v226, v207
	v_lshl_add_u64 v[208:209], v[130:131], 0, s[4:5]
	s_mov_b32 s4, 0x80000
	v_add_co_u32_e32 v228, vcc, s4, v130
	v_mul_f32_e32 v180, 0xbfb8aa3b, v52
	s_nop 0
	v_addc_co_u32_e32 v229, vcc, 0, v131, vcc
	s_waitcnt lgkmcnt(0)
	global_store_dwordx2 v[228:229], v[206:207], off
	v_mul_f32_e32 v206, 0xbfb8aa3b, v53
	v_mul_f32_e32 v207, 0xbfb8aa3b, v54
	v_exp_f32_e32 v180, v180
	v_exp_f32_e32 v206, v206
	v_exp_f32_e32 v207, v207
	v_rcp_f32_e32 v227, v227
	v_add_f32_e32 v180, 1.0, v180
	v_add_f32_e32 v206, 1.0, v206
	v_add_f32_e32 v207, 1.0, v207
	v_rcp_f32_e32 v180, v180
	v_rcp_f32_e32 v206, v206
	v_rcp_f32_e32 v207, v207
	s_mov_b64 s[4:5], 0x90000
	v_cvt_pk_bf16_f32 v180, v180, v206
	v_cvt_pk_bf16_f32 v207, v207, v227
	ds_bpermute_b32 v206, v226, v180
	ds_bpermute_b32 v207, v226, v207
	v_exp_f32_e32 v180, v146
	v_exp_f32_e32 v227, v141
	s_waitcnt lgkmcnt(0)
	global_store_dwordx2 v[208:209], v[206:207], off offset:32
	v_exp_f32_e32 v206, v145
	v_exp_f32_e32 v207, v144
	v_add_f32_e32 v180, 1.0, v180
	v_add_f32_e32 v227, 1.0, v227
	v_add_f32_e32 v206, 1.0, v206
	v_add_f32_e32 v207, 1.0, v207
	v_rcp_f32_e32 v180, v180
	v_rcp_f32_e32 v206, v206
	v_rcp_f32_e32 v207, v207
	v_rcp_f32_e32 v227, v227
	v_cvt_pk_bf16_f32 v180, v180, v206
	ds_bpermute_b32 v206, v226, v180
	v_cvt_pk_bf16_f32 v207, v207, v227
	ds_bpermute_b32 v207, v226, v207
	v_exp_f32_e32 v180, v140
	v_exp_f32_e32 v227, v137
	s_waitcnt lgkmcnt(0)
	global_store_dwordx2 v[208:209], v[206:207], off offset:256
	v_exp_f32_e32 v206, v139
	v_exp_f32_e32 v207, v138
	v_add_f32_e32 v180, 1.0, v180
	v_add_f32_e32 v227, 1.0, v227
	v_add_f32_e32 v206, 1.0, v206
	v_add_f32_e32 v207, 1.0, v207
	v_rcp_f32_e32 v180, v180
	v_rcp_f32_e32 v206, v206
	v_rcp_f32_e32 v207, v207
	v_rcp_f32_e32 v227, v227
	v_cvt_pk_bf16_f32 v180, v180, v206
	ds_bpermute_b32 v206, v226, v180
	v_cvt_pk_bf16_f32 v207, v207, v227
	ds_bpermute_b32 v207, v226, v207
	v_mul_f32_e32 v180, 0xbfb8aa3b, v44
	v_exp_f32_e32 v180, v180
	v_mul_f32_e32 v227, 0xbfb8aa3b, v39
	v_exp_f32_e32 v227, v227
	s_waitcnt lgkmcnt(0)
	global_store_dwordx2 v[208:209], v[206:207], off offset:288
	v_mul_f32_e32 v206, 0xbfb8aa3b, v45
	v_mul_f32_e32 v207, 0xbfb8aa3b, v46
	v_mul_f32_e32 v208, 0xbfb8aa3b, v47
	v_exp_f32_e32 v206, v206
	v_exp_f32_e32 v207, v207
	v_exp_f32_e32 v208, v208
	v_add_f32_e32 v180, 1.0, v180
	v_add_f32_e32 v206, 1.0, v206
	v_add_f32_e32 v207, 1.0, v207
	v_add_f32_e32 v208, 1.0, v208
	v_rcp_f32_e32 v180, v180
	v_rcp_f32_e32 v206, v206
	v_rcp_f32_e32 v207, v207
	v_rcp_f32_e32 v208, v208
	v_add_f32_e32 v227, 1.0, v227
	v_cvt_pk_bf16_f32 v180, v180, v206
	ds_bpermute_b32 v206, v226, v180
	v_cvt_pk_bf16_f32 v207, v207, v208
	ds_bpermute_b32 v207, v226, v207
	v_lshl_add_u64 v[208:209], v[130:131], 0, s[4:5]
	s_mov_b32 s4, 0x90000
	v_add_co_u32_e32 v228, vcc, s4, v130
	v_mul_f32_e32 v180, 0xbfb8aa3b, v36
	s_nop 0
	v_addc_co_u32_e32 v229, vcc, 0, v131, vcc
	s_waitcnt lgkmcnt(0)
	global_store_dwordx2 v[228:229], v[206:207], off
	v_mul_f32_e32 v206, 0xbfb8aa3b, v37
	v_mul_f32_e32 v207, 0xbfb8aa3b, v38
	v_exp_f32_e32 v180, v180
	v_exp_f32_e32 v206, v206
	v_exp_f32_e32 v207, v207
	v_rcp_f32_e32 v227, v227
	v_add_f32_e32 v180, 1.0, v180
	v_add_f32_e32 v206, 1.0, v206
	v_add_f32_e32 v207, 1.0, v207
	v_rcp_f32_e32 v180, v180
	v_rcp_f32_e32 v206, v206
	v_rcp_f32_e32 v207, v207
	s_mov_b64 s[4:5], 0xa0000
	v_cvt_pk_bf16_f32 v180, v180, v206
	v_cvt_pk_bf16_f32 v207, v207, v227
	ds_bpermute_b32 v206, v226, v180
	ds_bpermute_b32 v207, v226, v207
	v_exp_f32_e32 v180, v136
	v_exp_f32_e32 v227, v132
	s_waitcnt lgkmcnt(0)
	global_store_dwordx2 v[208:209], v[206:207], off offset:32
	v_exp_f32_e32 v206, v135
	v_exp_f32_e32 v207, v134
	v_add_f32_e32 v180, 1.0, v180
	v_add_f32_e32 v227, 1.0, v227
	v_add_f32_e32 v206, 1.0, v206
	v_add_f32_e32 v207, 1.0, v207
	v_rcp_f32_e32 v180, v180
	v_rcp_f32_e32 v206, v206
	v_rcp_f32_e32 v207, v207
	v_rcp_f32_e32 v227, v227
	v_cvt_pk_bf16_f32 v180, v180, v206
	ds_bpermute_b32 v206, v226, v180
	v_cvt_pk_bf16_f32 v207, v207, v227
	ds_bpermute_b32 v207, v226, v207
	v_mul_f32_e32 v180, 0xbfb8aa3b, v32
	v_mul_f32_e32 v227, 0xbfb8aa3b, v35
	v_exp_f32_e32 v180, v180
	v_exp_f32_e32 v227, v227
	s_waitcnt lgkmcnt(0)
	global_store_dwordx2 v[208:209], v[206:207], off offset:256
	v_mul_f32_e32 v206, 0xbfb8aa3b, v33
	v_mul_f32_e32 v207, 0xbfb8aa3b, v34
	v_exp_f32_e32 v206, v206
	v_exp_f32_e32 v207, v207
	v_add_f32_e32 v180, 1.0, v180
	v_add_f32_e32 v227, 1.0, v227
	v_add_f32_e32 v206, 1.0, v206
	v_add_f32_e32 v207, 1.0, v207
	v_rcp_f32_e32 v180, v180
	v_rcp_f32_e32 v206, v206
	v_rcp_f32_e32 v207, v207
	v_rcp_f32_e32 v227, v227
	v_cvt_pk_bf16_f32 v180, v180, v206
	ds_bpermute_b32 v206, v226, v180
	v_cvt_pk_bf16_f32 v207, v207, v227
	ds_bpermute_b32 v207, v226, v207
	v_mul_f32_e32 v180, 0xbfb8aa3b, v28
	v_exp_f32_e32 v180, v180
	v_mul_f32_e32 v227, 0xbfb8aa3b, v23
	v_exp_f32_e32 v227, v227
	s_waitcnt lgkmcnt(0)
	global_store_dwordx2 v[208:209], v[206:207], off offset:288
	v_mul_f32_e32 v206, 0xbfb8aa3b, v29
	v_mul_f32_e32 v207, 0xbfb8aa3b, v30
	v_mul_f32_e32 v208, 0xbfb8aa3b, v31
	v_exp_f32_e32 v206, v206
	v_exp_f32_e32 v207, v207
	v_exp_f32_e32 v208, v208
	v_add_f32_e32 v180, 1.0, v180
	v_add_f32_e32 v206, 1.0, v206
	v_add_f32_e32 v207, 1.0, v207
	v_add_f32_e32 v208, 1.0, v208
	v_rcp_f32_e32 v180, v180
	v_rcp_f32_e32 v206, v206
	v_rcp_f32_e32 v207, v207
	v_rcp_f32_e32 v208, v208
	v_add_f32_e32 v227, 1.0, v227
	v_cvt_pk_bf16_f32 v180, v180, v206
	ds_bpermute_b32 v206, v226, v180
	v_cvt_pk_bf16_f32 v207, v207, v208
	ds_bpermute_b32 v207, v226, v207
	v_lshl_add_u64 v[208:209], v[130:131], 0, s[4:5]
	s_mov_b32 s4, 0xa0000
	v_add_co_u32_e32 v228, vcc, s4, v130
	v_mul_f32_e32 v180, 0xbfb8aa3b, v20
	s_nop 0
	v_addc_co_u32_e32 v229, vcc, 0, v131, vcc
	s_waitcnt lgkmcnt(0)
	global_store_dwordx2 v[228:229], v[206:207], off
	v_mul_f32_e32 v206, 0xbfb8aa3b, v21
	v_mul_f32_e32 v207, 0xbfb8aa3b, v22
	v_exp_f32_e32 v180, v180
	v_exp_f32_e32 v206, v206
	v_exp_f32_e32 v207, v207
	v_rcp_f32_e32 v227, v227
	v_add_f32_e32 v180, 1.0, v180
	v_add_f32_e32 v206, 1.0, v206
	v_add_f32_e32 v207, 1.0, v207
	v_rcp_f32_e32 v180, v180
	v_rcp_f32_e32 v206, v206
	v_rcp_f32_e32 v207, v207
	s_mov_b64 s[4:5], 0xb0000
	v_cvt_pk_bf16_f32 v180, v180, v206
	v_cvt_pk_bf16_f32 v207, v207, v227
	ds_bpermute_b32 v206, v226, v180
	ds_bpermute_b32 v207, v226, v207
	v_mul_f32_e32 v180, 0xbfb8aa3b, v24
	v_mul_f32_e32 v227, 0xbfb8aa3b, v27
	v_exp_f32_e32 v180, v180
	v_exp_f32_e32 v227, v227
	s_waitcnt lgkmcnt(0)
	global_store_dwordx2 v[208:209], v[206:207], off offset:32
	v_mul_f32_e32 v206, 0xbfb8aa3b, v25
	v_mul_f32_e32 v207, 0xbfb8aa3b, v26
	v_exp_f32_e32 v206, v206
	v_exp_f32_e32 v207, v207
	v_add_f32_e32 v180, 1.0, v180
	v_add_f32_e32 v227, 1.0, v227
	v_add_f32_e32 v206, 1.0, v206
	v_add_f32_e32 v207, 1.0, v207
	v_rcp_f32_e32 v180, v180
	v_rcp_f32_e32 v206, v206
	v_rcp_f32_e32 v207, v207
	v_rcp_f32_e32 v227, v227
	v_cvt_pk_bf16_f32 v180, v180, v206
	ds_bpermute_b32 v206, v226, v180
	v_cvt_pk_bf16_f32 v207, v207, v227
	ds_bpermute_b32 v207, v226, v207
	v_mul_f32_e32 v180, 0xbfb8aa3b, v16
	v_mul_f32_e32 v227, 0xbfb8aa3b, v19
	v_exp_f32_e32 v180, v180
	v_exp_f32_e32 v227, v227
	s_waitcnt lgkmcnt(0)
	global_store_dwordx2 v[208:209], v[206:207], off offset:256
	v_mul_f32_e32 v206, 0xbfb8aa3b, v17
	v_mul_f32_e32 v207, 0xbfb8aa3b, v18
	v_exp_f32_e32 v206, v206
	v_exp_f32_e32 v207, v207
	v_add_f32_e32 v180, 1.0, v180
	v_add_f32_e32 v227, 1.0, v227
	v_add_f32_e32 v206, 1.0, v206
	v_add_f32_e32 v207, 1.0, v207
	v_rcp_f32_e32 v180, v180
	v_rcp_f32_e32 v206, v206
	v_rcp_f32_e32 v207, v207
	v_rcp_f32_e32 v227, v227
	v_cvt_pk_bf16_f32 v180, v180, v206
	ds_bpermute_b32 v206, v226, v180
	v_cvt_pk_bf16_f32 v207, v207, v227
	ds_bpermute_b32 v207, v226, v207
	v_mul_f32_e32 v180, 0xbfb8aa3b, v12
	v_exp_f32_e32 v180, v180
	s_waitcnt lgkmcnt(0)
	global_store_dwordx2 v[208:209], v[206:207], off offset:288
	v_mul_f32_e32 v206, 0xbfb8aa3b, v13
	v_mul_f32_e32 v207, 0xbfb8aa3b, v14
	v_mul_f32_e32 v208, 0xbfb8aa3b, v15
	v_exp_f32_e32 v206, v206
	v_exp_f32_e32 v207, v207
	v_exp_f32_e32 v208, v208
	v_add_f32_e32 v180, 1.0, v180
	v_add_f32_e32 v206, 1.0, v206
	v_add_f32_e32 v207, 1.0, v207
	v_add_f32_e32 v208, 1.0, v208
	v_rcp_f32_e32 v180, v180
	v_rcp_f32_e32 v206, v206
	v_rcp_f32_e32 v207, v207
	v_rcp_f32_e32 v208, v208
	v_cvt_pk_bf16_f32 v180, v180, v206
	ds_bpermute_b32 v206, v226, v180
	v_cvt_pk_bf16_f32 v207, v207, v208
	ds_bpermute_b32 v207, v226, v207
	v_lshl_add_u64 v[208:209], v[130:131], 0, s[4:5]
	s_mov_b32 s4, 0xb0000
	v_add_co_u32_e32 v130, vcc, s4, v130
	v_mul_f32_e32 v180, 0xbfb8aa3b, v6
	s_nop 0
	v_addc_co_u32_e32 v131, vcc, 0, v131, vcc
	s_waitcnt lgkmcnt(0)
	global_store_dwordx2 v[130:131], v[206:207], off
	v_mul_f32_e32 v130, 0xbfb8aa3b, v4
	v_mul_f32_e32 v131, 0xbfb8aa3b, v5
	v_mul_f32_e32 v206, 0xbfb8aa3b, v7
	v_exp_f32_e32 v130, v130
	v_exp_f32_e32 v131, v131
	v_exp_f32_e32 v180, v180
	v_exp_f32_e32 v206, v206
	v_add_f32_e32 v130, 1.0, v130
	v_add_f32_e32 v131, 1.0, v131
	v_add_f32_e32 v180, 1.0, v180
	v_add_f32_e32 v206, 1.0, v206
	v_rcp_f32_e32 v130, v130
	v_rcp_f32_e32 v131, v131
	v_rcp_f32_e32 v180, v180
	v_rcp_f32_e32 v206, v206
	s_mov_b64 s[4:5], 0
	v_cvt_pk_bf16_f32 v130, v130, v131
	ds_bpermute_b32 v130, v226, v130
	v_cvt_pk_bf16_f32 v131, v180, v206
	ds_bpermute_b32 v131, v226, v131
	v_mul_f32_e32 v180, 0xbfb8aa3b, v10
	v_mul_f32_e32 v206, 0xbfb8aa3b, v11
	v_exp_f32_e32 v180, v180
	v_exp_f32_e32 v206, v206
	s_waitcnt lgkmcnt(0)
	global_store_dwordx2 v[208:209], v[130:131], off offset:32
	v_mul_f32_e32 v130, 0xbfb8aa3b, v8
	v_mul_f32_e32 v131, 0xbfb8aa3b, v9
	v_exp_f32_e32 v130, v130
	v_exp_f32_e32 v131, v131
	v_add_f32_e32 v180, 1.0, v180
	v_add_f32_e32 v206, 1.0, v206
	v_add_f32_e32 v130, 1.0, v130
	v_add_f32_e32 v131, 1.0, v131
	v_rcp_f32_e32 v130, v130
	v_rcp_f32_e32 v131, v131
	v_rcp_f32_e32 v180, v180
	v_rcp_f32_e32 v206, v206
	v_cvt_pk_bf16_f32 v130, v130, v131
	ds_bpermute_b32 v130, v226, v130
	v_cvt_pk_bf16_f32 v131, v180, v206
	ds_bpermute_b32 v131, v226, v131
	v_mul_f32_e32 v180, 0xbfb8aa3b, v2
	v_mul_f32_e32 v206, 0xbfb8aa3b, v3
	v_exp_f32_e32 v180, v180
	v_exp_f32_e32 v206, v206
	s_waitcnt lgkmcnt(0)
	global_store_dwordx2 v[208:209], v[130:131], off offset:256
	v_mul_f32_e32 v130, 0xbfb8aa3b, v0
	v_mul_f32_e32 v131, 0xbfb8aa3b, v1
	v_exp_f32_e32 v130, v130
	v_exp_f32_e32 v131, v131
	v_add_f32_e32 v180, 1.0, v180
	v_add_f32_e32 v206, 1.0, v206
	v_add_f32_e32 v130, 1.0, v130
	v_add_f32_e32 v131, 1.0, v131
	v_rcp_f32_e32 v130, v130
	v_rcp_f32_e32 v131, v131
	v_rcp_f32_e32 v180, v180
	v_rcp_f32_e32 v206, v206
	v_cvt_pk_bf16_f32 v130, v130, v131
	ds_bpermute_b32 v130, v226, v130
	v_cvt_pk_bf16_f32 v131, v180, v206
	ds_bpermute_b32 v131, v226, v131
	s_waitcnt lgkmcnt(0)
	global_store_dwordx2 v[208:209], v[130:131], off offset:288

.LBB0_1024:
	s_waitcnt lgkmcnt(0)
	ds_read_b128 v[128:131], v179
	ds_read_b128 v[132:135], v179 offset:1024
	ds_read_b128 v[136:139], v179 offset:2048
	ds_read_b128 v[140:143], v179 offset:3072
	s_add_i32 s62, s36, 2
	s_add_u32 s37, s4, 0xfff80080
	s_addc_u32 s38, s5, -1
	s_cmp_eq_u32 s59, s36
	s_cselect_b32 s36, s58, s60
	s_cselect_b32 s39, s21, s38
	s_cselect_b32 s38, s25, s37
	s_cselect_b32 s37, s23, s61

	s_add_i32 m0, s31, 0xc000
	ds_read_b128 v[144:147], v190
	ds_read_b128 v[148:151], v190 offset:1024
	ds_read_b128 v[152:155], v190 offset:2048
	ds_read_b128 v[156:159], v190 offset:3072
	ds_read_b128 v[180:183], v190 offset:4096
	ds_read_b128 v[184:187], v190 offset:5120
	ds_read_b128 v[194:197], v190 offset:6144

	global_load_lds_dwordx4 v162, s[4:5]
	s_add_i32 m0, s31, 0xe000
	ds_read_b128 v[198:201], v190 offset:7168

	global_load_lds_dwordx4 v164, s[4:5]
	s_waitcnt lgkmcnt(8)
	s_barrier
	s_waitcnt lgkmcnt(0)


	v_mfma_f32_16x16x32_bf16 v[124:127], v[128:131], v[144:147], v[124:127]
	v_mfma_f32_16x16x32_bf16 v[120:123], v[136:139], v[144:147], v[120:123]
	v_mfma_f32_16x16x32_bf16 v[116:119], v[128:131], v[152:155], v[116:119]
	v_mfma_f32_16x16x32_bf16 v[104:107], v[136:139], v[152:155], v[104:107]
	v_mfma_f32_16x16x32_bf16 v[96:99], v[128:131], v[180:183], v[96:99]
	v_mfma_f32_16x16x32_bf16 v[88:91], v[136:139], v[180:183], v[88:91]
	v_mfma_f32_16x16x32_bf16 v[80:83], v[128:131], v[194:197], v[80:83]
	v_mfma_f32_16x16x32_bf16 v[72:75], v[136:139], v[194:197], v[72:75]
	v_mfma_f32_16x16x32_bf16 v[124:127], v[132:135], v[148:151], v[124:127]
	v_mfma_f32_16x16x32_bf16 v[120:123], v[140:143], v[148:151], v[120:123]
	v_mfma_f32_16x16x32_bf16 v[116:119], v[132:135], v[156:159], v[116:119]
	v_mfma_f32_16x16x32_bf16 v[104:107], v[140:143], v[156:159], v[104:107]
	v_mfma_f32_16x16x32_bf16 v[96:99], v[132:135], v[184:187], v[96:99]
	v_mfma_f32_16x16x32_bf16 v[88:91], v[140:143], v[184:187], v[88:91]
	v_mfma_f32_16x16x32_bf16 v[80:83], v[132:135], v[198:201], v[80:83]
	v_mfma_f32_16x16x32_bf16 v[72:75], v[140:143], v[198:201], v[72:75]

	s_barrier
	s_add_i32 s63, s52, s42
	s_add_u32 s66, s36, s14
	s_addc_u32 s67, s37, s15
	s_mov_b32 m0, s63
	ds_read_b128 v[202:205], v191
	ds_read_b128 v[206:209], v191 offset:1024
	ds_read_b128 v[222:225], v191 offset:2048

	global_load_lds_dwordx4 v172, s[36:37]
	s_add_i32 m0, s63, 0x2000
	ds_read_b128 v[226:229], v191 offset:3072

	global_load_lds_dwordx4 v174, s[36:37]
	s_barrier
	s_waitcnt lgkmcnt(0)


	v_mfma_f32_16x16x32_bf16 v[112:115], v[202:205], v[144:147], v[112:115]
	v_mfma_f32_16x16x32_bf16 v[108:111], v[222:225], v[144:147], v[108:111]
	v_mfma_f32_16x16x32_bf16 v[100:103], v[202:205], v[152:155], v[100:103]
	v_mfma_f32_16x16x32_bf16 v[92:95], v[222:225], v[152:155], v[92:95]
	v_mfma_f32_16x16x32_bf16 v[84:87], v[202:205], v[180:183], v[84:87]
	v_mfma_f32_16x16x32_bf16 v[76:79], v[222:225], v[180:183], v[76:79]
	v_mfma_f32_16x16x32_bf16 v[68:71], v[202:205], v[194:197], v[68:71]
	v_mfma_f32_16x16x32_bf16 v[64:67], v[222:225], v[194:197], v[64:67]
	v_mfma_f32_16x16x32_bf16 v[112:115], v[206:209], v[148:151], v[112:115]
	v_mfma_f32_16x16x32_bf16 v[108:111], v[226:229], v[148:151], v[108:111]
	v_mfma_f32_16x16x32_bf16 v[100:103], v[206:209], v[156:159], v[100:103]
	v_mfma_f32_16x16x32_bf16 v[92:95], v[226:229], v[156:159], v[92:95]
	v_mfma_f32_16x16x32_bf16 v[84:87], v[206:209], v[184:187], v[84:87]
	v_mfma_f32_16x16x32_bf16 v[76:79], v[226:229], v[184:187], v[76:79]
	v_mfma_f32_16x16x32_bf16 v[68:71], v[206:209], v[198:201], v[68:71]
	v_mfma_f32_16x16x32_bf16 v[64:67], v[226:229], v[198:201], v[64:67]

	s_mov_b32 m0, s31
	s_add_u32 s68, s38, s14
	s_addc_u32 s69, s39, s15
	s_barrier
	ds_read_b128 v[144:147], v190 offset:16384
	ds_read_b128 v[148:151], v190 offset:17408
	ds_read_b128 v[152:155], v190 offset:18432
	ds_read_b128 v[156:159], v190 offset:19456
	ds_read_b128 v[180:183], v190 offset:20480
	ds_read_b128 v[184:187], v190 offset:21504
	ds_read_b128 v[194:197], v190 offset:22528

	global_load_lds_dwordx4 v172, s[38:39]
	s_mov_b32 m0, s35
	ds_read_b128 v[198:201], v190 offset:23552

	global_load_lds_dwordx4 v174, s[38:39]
	s_barrier
	s_waitcnt lgkmcnt(0)


	v_mfma_f32_16x16x32_bf16 v[60:63], v[128:131], v[144:147], v[60:63]
	v_mfma_f32_16x16x32_bf16 v[56:59], v[136:139], v[144:147], v[56:59]
	v_mfma_f32_16x16x32_bf16 v[52:55], v[128:131], v[152:155], v[52:55]
	v_mfma_f32_16x16x32_bf16 v[40:43], v[136:139], v[152:155], v[40:43]
	v_mfma_f32_16x16x32_bf16 v[36:39], v[128:131], v[180:183], v[36:39]
	v_mfma_f32_16x16x32_bf16 v[24:27], v[136:139], v[180:183], v[24:27]
	v_mfma_f32_16x16x32_bf16 v[20:23], v[128:131], v[194:197], v[20:23]
	v_mfma_f32_16x16x32_bf16 v[8:11], v[136:139], v[194:197], v[8:11]
	v_mfma_f32_16x16x32_bf16 v[60:63], v[132:135], v[148:151], v[60:63]
	v_mfma_f32_16x16x32_bf16 v[56:59], v[140:143], v[148:151], v[56:59]
	v_mfma_f32_16x16x32_bf16 v[52:55], v[132:135], v[156:159], v[52:55]
	v_mfma_f32_16x16x32_bf16 v[40:43], v[140:143], v[156:159], v[40:43]
	v_mfma_f32_16x16x32_bf16 v[36:39], v[132:135], v[184:187], v[36:39]
	v_mfma_f32_16x16x32_bf16 v[24:27], v[140:143], v[184:187], v[24:27]
	v_mfma_f32_16x16x32_bf16 v[20:23], v[132:135], v[198:201], v[20:23]
	v_mfma_f32_16x16x32_bf16 v[8:11], v[140:143], v[198:201], v[8:11]

	s_barrier
	s_add_i32 s63, s53, s42
	s_mov_b32 m0, s63
	s_add_u32 s64, s36, 0x80000
	s_addc_u32 s65, s37, 0


	global_load_lds_dwordx4 v172, s[64:65]
	s_add_i32 m0, s63, 0x2000
	s_nop 0

	global_load_lds_dwordx4 v174, s[64:65]
	s_waitcnt vmcnt(6)
	s_barrier

	v_mfma_f32_16x16x32_bf16 v[48:51], v[202:205], v[144:147], v[48:51]
	v_mfma_f32_16x16x32_bf16 v[44:47], v[222:225], v[144:147], v[44:47]
	v_mfma_f32_16x16x32_bf16 v[32:35], v[202:205], v[152:155], v[32:35]
	v_mfma_f32_16x16x32_bf16 v[28:31], v[222:225], v[152:155], v[28:31]
	v_mfma_f32_16x16x32_bf16 v[16:19], v[202:205], v[180:183], v[16:19]
	v_mfma_f32_16x16x32_bf16 v[12:15], v[222:225], v[180:183], v[12:15]
	v_mfma_f32_16x16x32_bf16 v[4:7], v[202:205], v[194:197], v[4:7]
	v_mfma_f32_16x16x32_bf16 v[0:3], v[222:225], v[194:197], v[0:3]
	v_mfma_f32_16x16x32_bf16 v[48:51], v[206:209], v[148:151], v[48:51]
	v_mfma_f32_16x16x32_bf16 v[44:47], v[226:229], v[148:151], v[44:47]
	v_mfma_f32_16x16x32_bf16 v[32:35], v[206:209], v[156:159], v[32:35]
	v_mfma_f32_16x16x32_bf16 v[28:31], v[226:229], v[156:159], v[28:31]
	v_mfma_f32_16x16x32_bf16 v[16:19], v[206:209], v[184:187], v[16:19]
	v_mfma_f32_16x16x32_bf16 v[12:15], v[226:229], v[184:187], v[12:15]
	v_mfma_f32_16x16x32_bf16 v[4:7], v[206:209], v[198:201], v[4:7]
	v_mfma_f32_16x16x32_bf16 v[0:3], v[226:229], v[198:201], v[0:3]

	s_add_i32 s63, 0, 0x18000

	s_barrier
	ds_read_b128 v[128:131], v179 offset:32768
	ds_read_b128 v[132:135], v179 offset:33792
	ds_read_b128 v[136:139], v179 offset:34816
	ds_read_b128 v[140:143], v179 offset:35840
	s_add_u32 s38, s38, 0x80000
	s_addc_u32 s39, s39, 0
	s_mov_b32 m0, s43

	ds_read_b128 v[144:147], v190 offset:32768
	ds_read_b128 v[148:151], v190 offset:33792
	ds_read_b128 v[152:155], v190 offset:34816
	ds_read_b128 v[156:159], v190 offset:35840
	ds_read_b128 v[180:183], v190 offset:36864
	ds_read_b128 v[184:187], v190 offset:37888
	ds_read_b128 v[194:197], v190 offset:38912

	global_load_lds_dwordx4 v172, s[38:39]
	s_mov_b32 m0, s44
	ds_read_b128 v[198:201], v190 offset:39936

	global_load_lds_dwordx4 v174, s[38:39]
	s_waitcnt lgkmcnt(8)
	s_barrier
	s_waitcnt lgkmcnt(0)


	v_mfma_f32_16x16x32_bf16 v[124:127], v[128:131], v[144:147], v[124:127]
	v_mfma_f32_16x16x32_bf16 v[120:123], v[136:139], v[144:147], v[120:123]
	v_mfma_f32_16x16x32_bf16 v[116:119], v[128:131], v[152:155], v[116:119]
	v_mfma_f32_16x16x32_bf16 v[104:107], v[136:139], v[152:155], v[104:107]
	v_mfma_f32_16x16x32_bf16 v[96:99], v[128:131], v[180:183], v[96:99]
	v_mfma_f32_16x16x32_bf16 v[88:91], v[136:139], v[180:183], v[88:91]
	v_mfma_f32_16x16x32_bf16 v[80:83], v[128:131], v[194:197], v[80:83]
	v_mfma_f32_16x16x32_bf16 v[72:75], v[136:139], v[194:197], v[72:75]
	v_mfma_f32_16x16x32_bf16 v[124:127], v[132:135], v[148:151], v[124:127]
	v_mfma_f32_16x16x32_bf16 v[120:123], v[140:143], v[148:151], v[120:123]
	v_mfma_f32_16x16x32_bf16 v[116:119], v[132:135], v[156:159], v[116:119]
	v_mfma_f32_16x16x32_bf16 v[104:107], v[140:143], v[156:159], v[104:107]
	v_mfma_f32_16x16x32_bf16 v[96:99], v[132:135], v[184:187], v[96:99]
	v_mfma_f32_16x16x32_bf16 v[88:91], v[140:143], v[184:187], v[88:91]
	v_mfma_f32_16x16x32_bf16 v[80:83], v[132:135], v[198:201], v[80:83]
	v_mfma_f32_16x16x32_bf16 v[72:75], v[140:143], v[198:201], v[72:75]

	s_barrier
	s_add_i32 s38, 0, 0x1c000
	s_add_i32 s39, s63, s42


	s_mov_b32 m0, s39
	ds_read_b128 v[202:205], v191 offset:32768
	ds_read_b128 v[206:209], v191 offset:33792
	ds_read_b128 v[222:225], v191 offset:34816

	global_load_lds_dwordx4 v172, s[66:67]
	s_add_i32 m0, s39, 0x2000
	ds_read_b128 v[226:229], v191 offset:35840

	global_load_lds_dwordx4 v174, s[66:67]
	s_barrier
	s_waitcnt lgkmcnt(0)


	v_mfma_f32_16x16x32_bf16 v[112:115], v[202:205], v[144:147], v[112:115]
	v_mfma_f32_16x16x32_bf16 v[108:111], v[222:225], v[144:147], v[108:111]
	v_mfma_f32_16x16x32_bf16 v[100:103], v[202:205], v[152:155], v[100:103]
	v_mfma_f32_16x16x32_bf16 v[92:95], v[222:225], v[152:155], v[92:95]
	v_mfma_f32_16x16x32_bf16 v[84:87], v[202:205], v[180:183], v[84:87]
	v_mfma_f32_16x16x32_bf16 v[76:79], v[222:225], v[180:183], v[76:79]
	v_mfma_f32_16x16x32_bf16 v[68:71], v[202:205], v[194:197], v[68:71]
	v_mfma_f32_16x16x32_bf16 v[64:67], v[222:225], v[194:197], v[64:67]
	v_mfma_f32_16x16x32_bf16 v[112:115], v[206:209], v[148:151], v[112:115]
	v_mfma_f32_16x16x32_bf16 v[108:111], v[226:229], v[148:151], v[108:111]
	v_mfma_f32_16x16x32_bf16 v[100:103], v[206:209], v[156:159], v[100:103]
	v_mfma_f32_16x16x32_bf16 v[92:95], v[226:229], v[156:159], v[92:95]
	v_mfma_f32_16x16x32_bf16 v[84:87], v[206:209], v[184:187], v[84:87]
	v_mfma_f32_16x16x32_bf16 v[76:79], v[226:229], v[184:187], v[76:79]
	v_mfma_f32_16x16x32_bf16 v[68:71], v[206:209], v[198:201], v[68:71]
	v_mfma_f32_16x16x32_bf16 v[64:67], v[226:229], v[198:201], v[64:67]

	s_mov_b32 m0, s48

	s_barrier
	ds_read_b128 v[144:147], v190 offset:49152
	ds_read_b128 v[148:151], v190 offset:50176
	ds_read_b128 v[152:155], v190 offset:51200
	ds_read_b128 v[156:159], v190 offset:52224
	ds_read_b128 v[180:183], v190 offset:53248
	ds_read_b128 v[184:187], v190 offset:54272
	ds_read_b128 v[194:197], v190 offset:55296

	global_load_lds_dwordx4 v172, s[68:69]
	s_mov_b32 m0, s49
	ds_read_b128 v[198:201], v190 offset:56320

	global_load_lds_dwordx4 v174, s[68:69]
	s_barrier
	s_waitcnt lgkmcnt(0)


	v_mfma_f32_16x16x32_bf16 v[60:63], v[128:131], v[144:147], v[60:63]
	v_mfma_f32_16x16x32_bf16 v[56:59], v[136:139], v[144:147], v[56:59]
	v_mfma_f32_16x16x32_bf16 v[52:55], v[128:131], v[152:155], v[52:55]
	v_mfma_f32_16x16x32_bf16 v[40:43], v[136:139], v[152:155], v[40:43]
	v_mfma_f32_16x16x32_bf16 v[36:39], v[128:131], v[180:183], v[36:39]
	v_mfma_f32_16x16x32_bf16 v[24:27], v[136:139], v[180:183], v[24:27]
	v_mfma_f32_16x16x32_bf16 v[20:23], v[128:131], v[194:197], v[20:23]
	v_mfma_f32_16x16x32_bf16 v[8:11], v[136:139], v[194:197], v[8:11]
	v_mfma_f32_16x16x32_bf16 v[60:63], v[132:135], v[148:151], v[60:63]
	v_mfma_f32_16x16x32_bf16 v[56:59], v[140:143], v[148:151], v[56:59]
	v_mfma_f32_16x16x32_bf16 v[52:55], v[132:135], v[156:159], v[52:55]
	v_mfma_f32_16x16x32_bf16 v[40:43], v[140:143], v[156:159], v[40:43]
	v_mfma_f32_16x16x32_bf16 v[36:39], v[132:135], v[184:187], v[36:39]
	v_mfma_f32_16x16x32_bf16 v[24:27], v[140:143], v[184:187], v[24:27]
	v_mfma_f32_16x16x32_bf16 v[20:23], v[132:135], v[198:201], v[20:23]
	v_mfma_f32_16x16x32_bf16 v[8:11], v[140:143], v[198:201], v[8:11]

	s_barrier
	s_add_u32 s36, s36, 0x80080
	s_addc_u32 s37, s37, 0
	s_add_i32 s38, s38, s42
	s_mov_b32 m0, s38
	s_add_u32 s4, s4, 0x100
	s_addc_u32 s5, s5, 0

	global_load_lds_dwordx4 v172, s[36:37]
	s_add_i32 m0, s38, 0x2000
	s_add_u32 s60, s60, 0x100
	s_addc_u32 s61, s61, 0

	global_load_lds_dwordx4 v174, s[36:37]
	s_waitcnt vmcnt(6)
	s_barrier

	v_mfma_f32_16x16x32_bf16 v[48:51], v[202:205], v[144:147], v[48:51]
	v_mfma_f32_16x16x32_bf16 v[44:47], v[222:225], v[144:147], v[44:47]
	v_mfma_f32_16x16x32_bf16 v[32:35], v[202:205], v[152:155], v[32:35]
	v_mfma_f32_16x16x32_bf16 v[28:31], v[222:225], v[152:155], v[28:31]
	v_mfma_f32_16x16x32_bf16 v[16:19], v[202:205], v[180:183], v[16:19]
	v_mfma_f32_16x16x32_bf16 v[12:15], v[222:225], v[180:183], v[12:15]
	v_mfma_f32_16x16x32_bf16 v[4:7], v[202:205], v[194:197], v[4:7]
	v_mfma_f32_16x16x32_bf16 v[0:3], v[222:225], v[194:197], v[0:3]
	v_mfma_f32_16x16x32_bf16 v[48:51], v[206:209], v[148:151], v[48:51]
	v_mfma_f32_16x16x32_bf16 v[44:47], v[226:229], v[148:151], v[44:47]
	v_mfma_f32_16x16x32_bf16 v[32:35], v[206:209], v[156:159], v[32:35]
	v_mfma_f32_16x16x32_bf16 v[28:31], v[226:229], v[156:159], v[28:31]
	v_mfma_f32_16x16x32_bf16 v[16:19], v[206:209], v[184:187], v[16:19]
	v_mfma_f32_16x16x32_bf16 v[12:15], v[226:229], v[184:187], v[12:15]
	v_mfma_f32_16x16x32_bf16 v[4:7], v[206:209], v[198:201], v[4:7]
	v_mfma_f32_16x16x32_bf16 v[0:3], v[226:229], v[198:201], v[0:3]


	s_cmp_ge_i32 s62, s17
	s_mov_b32 s36, s62
	s_barrier
	s_cbranch_scc0 .LBB0_1024
	v_mov_b32_e32 v128, v210
	v_mov_b32_e32 v129, v169
	s_cmp_lt_i32 s12, 0
	v_lshl_add_u32 v128, v128, 4, v129
	v_ashrrev_i32_e32 v166, 2, v128
	v_and_b32_e32 v160, 3, v129
	v_and_b32_e32 v128, -4, v128
	v_lshl_add_u32 v193, v160, 6, v128
	s_mov_b64 s[4:5], -1
	s_cbranch_scc0 .LBB0_1043
	s_lshl_b32 s4, s30, 8
	v_lshl_or_b32 v128, v160, 2, s4
	s_lshl_b32 s4, s34, 8
	v_or_b32_e32 v180, s47, v128
	s_add_i32 s4, s4, s46
	v_readlane_b32 s60, v254, 6
	v_ashrrev_i32_e32 v181, 31, v180
	v_add_u32_e32 v184, s4, v166
	s_cmp_lt_i32 s34, 32
	v_readlane_b32 s61, v254, 7
	v_lshlrev_b64 v[128:129], 2, v[180:181]
	v_readlane_b32 s62, v254, 8
	v_readlane_b32 s63, v254, 9
	v_readlane_b32 s64, v254, 10
	v_readlane_b32 s65, v254, 11
	v_readlane_b32 s66, v254, 12
	v_readlane_b32 s67, v254, 13
	v_readlane_b32 s68, v254, 14
	v_readlane_b32 s69, v254, 15
	v_readlane_b32 s70, v254, 16
	v_readlane_b32 s71, v254, 17
	v_readlane_b32 s72, v254, 18
	v_readlane_b32 s73, v254, 19
	v_readlane_b32 s74, v254, 20
	v_readlane_b32 s75, v254, 21
	s_cselect_b32 s5, s61, s51
	s_cselect_b32 s4, s60, s50
	v_ashrrev_i32_e32 v185, 31, v184
	v_lshl_add_u64 v[182:183], s[4:5], 0, v[128:129]
	v_lshlrev_b64 v[130:131], 13, v[184:185]
	v_readlane_b32 s60, v254, 22
	v_lshl_add_u64 v[136:137], v[182:183], 0, v[130:131]
	v_readlane_b32 s61, v254, 23
	v_readlane_b32 s68, v254, 30
	v_readlane_b32 s69, v254, 31
	global_load_dwordx4 v[196:199], v[136:137], off nt
	global_load_dwordx4 v[200:203], v[136:137], off offset:64 nt
	global_load_dwordx4 v[204:207], v[136:137], off offset:512 nt
	s_mov_b64 s[60:61], s[68:69]
	v_lshl_add_u64 v[138:139], s[60:61], 0, v[128:129]
	global_load_dwordx4 v[140:143], v[138:139], off
	global_load_dwordx4 v[132:135], v[138:139], off offset:64
	global_load_dwordx4 v[128:131], v[138:139], off offset:512
	global_load_dwordx4 v[222:225], v[136:137], off offset:576 nt
	v_and_b32_e32 v145, 64, v192
	global_load_dwordx4 v[136:139], v[138:139], off offset:576
	v_xor_b32_e32 v144, 1, v192
	v_add_u32_e32 v194, 64, v145
	v_add_u32_e32 v186, 16, v184
	v_cmp_lt_i32_e64 s[4:5], v144, v194
	v_ashrrev_i32_e32 v187, 31, v186
	ds_bpermute_b32 v188, v193, v124
	v_cndmask_b32_e64 v195, v192, v144, s[4:5]
	v_lshlrev_b64 v[144:145], 13, v[186:187]
	v_lshl_add_u64 v[144:145], v[182:183], 0, v[144:145]
	global_load_dwordx4 v[156:159], v[144:145], off nt
	global_load_dwordx4 v[152:155], v[144:145], off offset:64 nt
	global_load_dwordx4 v[148:151], v[144:145], off offset:512 nt
	s_nop 0
	global_load_dwordx4 v[144:147], v[144:145], off offset:576 nt
	ds_bpermute_b32 v189, v193, v125
	ds_bpermute_b32 v208, v193, v126
	ds_bpermute_b32 v209, v193, v127
	ds_bpermute_b32 v226, v193, v120
	ds_bpermute_b32 v227, v193, v121
	ds_bpermute_b32 v228, v193, v122
	ds_bpermute_b32 v229, v193, v123
	ds_bpermute_b32 v230, v193, v112
	ds_bpermute_b32 v231, v193, v113
	v_readlane_b32 s64, v254, 26
	v_readlane_b32 s65, v254, 27
	v_readlane_b32 s66, v254, 28
	v_readlane_b32 s67, v254, 29
	v_readlane_b32 s72, v254, 34
	v_readlane_b32 s73, v254, 35
	v_readlane_b32 s74, v254, 36
	v_readlane_b32 s75, v254, 37
	s_mov_b64 s[64:65], s[72:73]
	ds_bpermute_b32 v232, v193, v114
	ds_bpermute_b32 v233, v193, v115
	v_lshlrev_b64 v[234:235], 11, v[184:185]
	s_mov_b64 s[66:67], s[74:75]
	v_lshl_add_u64 v[234:235], v[234:235], 0, v[180:181]
	v_xor_b32_e32 v167, 2, v192
	v_lshl_add_u64 v[236:237], v[234:235], 2, s[66:67]
	v_readlane_b32 s2, v254, 54
	v_cmp_lt_i32_e64 s[4:5], v167, v194
	v_lshlrev_b32_e32 v194, 2, v195
	v_lshlrev_b64 v[234:235], 1, v[234:235]
	v_readlane_b32 s3, v254, 55
	v_or_b32_e32 v240, 32, v234
	v_mov_b32_e32 v241, v235
	v_lshl_add_u64 v[238:239], s[2:3], 0, v[234:235]
	v_lshl_add_u64 v[240:241], s[2:3], 0, v[240:241]
	v_cndmask_b32_e64 v167, v192, v167, s[4:5]
	v_lshlrev_b32_e32 v167, 2, v167
	v_cmp_eq_u32_e32 vcc, 0, v160
	v_readlane_b32 s62, v254, 24
	v_readlane_b32 s63, v254, 25
	v_readlane_b32 s70, v254, 32
	v_readlane_b32 s71, v254, 33
	s_waitcnt vmcnt(0) lgkmcnt(0)
	v_pk_add_f32 v[198:199], v[198:199], v[208:209]
	v_pk_add_f32 v[196:197], v[196:197], v[188:189]
	v_pk_add_f32 v[202:203], v[202:203], v[228:229]
	v_pk_add_f32 v[200:201], v[200:201], v[226:227]
	v_pk_add_f32 v[204:205], v[204:205], v[230:231]
	v_mul_f32_e32 v195, v197, v197
	v_mul_f32_e32 v221, v199, v199
	global_store_dwordx4 v[236:237], v[196:199], off
	v_pk_mul_f32 v[188:189], v[142:143], v[198:199]
	v_pk_mul_f32 v[208:209], v[140:141], v[196:197]
	v_mul_f32_e32 v199, v201, v201
	v_mul_f32_e32 v230, v203, v203
	v_pk_mul_f32 v[226:227], v[134:135], v[202:203]
	v_pk_mul_f32 v[228:229], v[132:133], v[200:201]
	v_fmac_f32_e32 v195, v196, v196
	v_fmac_f32_e32 v221, v198, v198
	v_cvt_pk_bf16_f32 v196, v208, v209
	v_cvt_pk_bf16_f32 v197, v188, v189
	v_fmac_f32_e32 v199, v200, v200
	v_fmac_f32_e32 v230, v202, v202
	v_pk_add_f32 v[206:207], v[206:207], v[232:233]
	v_cvt_pk_bf16_f32 v188, v228, v229
	v_cvt_pk_bf16_f32 v189, v226, v227
	v_add_f32_e32 v195, v195, v221
	global_store_dwordx2 v[238:239], v[196:197], off
	v_add_f32_e32 v196, v199, v230
	global_store_dwordx4 v[236:237], v[200:203], off offset:64
	global_store_dwordx2 v[240:241], v[188:189], off
	v_add_f32_e32 v188, v195, v196
	v_mul_f32_e32 v189, v205, v205
	v_mul_f32_e32 v195, v207, v207
	v_fmac_f32_e32 v189, v204, v204
	v_fmac_f32_e32 v195, v206, v206
	ds_bpermute_b32 v200, v193, v108
	ds_bpermute_b32 v198, v193, v110
	ds_bpermute_b32 v199, v193, v111
	ds_bpermute_b32 v201, v193, v109
	v_add_f32_e32 v189, v189, v195
	v_add_f32_e32 v195, v188, v189
	v_pk_mul_f32 v[188:189], v[130:131], v[206:207]
	v_pk_mul_f32 v[196:197], v[128:129], v[204:205]
	global_store_dwordx4 v[236:237], v[204:207], off offset:512
	v_cvt_pk_bf16_f32 v196, v196, v197
	v_cvt_pk_bf16_f32 v197, v188, v189
	v_or_b32_e32 v188, 0x100, v234
	v_mov_b32_e32 v189, v235
	v_lshl_add_u64 v[188:189], s[2:3], 0, v[188:189]
	global_store_dwordx2 v[188:189], v[196:197], off
	s_waitcnt lgkmcnt(1)
	v_pk_add_f32 v[198:199], v[224:225], v[198:199]
	s_waitcnt lgkmcnt(0)
	v_pk_add_f32 v[196:197], v[222:223], v[200:201]
	v_mul_f32_e32 v189, v199, v199
	v_mul_f32_e32 v188, v197, v197
	v_fmac_f32_e32 v188, v196, v196
	v_fmac_f32_e32 v189, v198, v198
	v_add_f32_e32 v188, v188, v189
	v_add_f32_e32 v195, v195, v188
	ds_bpermute_b32 v200, v194, v195
	v_pk_mul_f32 v[188:189], v[136:137], v[196:197]
	global_store_dwordx4 v[236:237], v[196:199], off offset:576
	v_or_b32_e32 v234, 0x120, v234
	s_nop 0
	v_cvt_pk_bf16_f32 v196, v188, v189
	s_waitcnt lgkmcnt(0)
	v_add_f32_e32 v188, v195, v200
	ds_bpermute_b32 v189, v167, v188
	v_pk_mul_f32 v[198:199], v[138:139], v[198:199]
	s_nop 0
	v_cvt_pk_bf16_f32 v197, v198, v199
	v_lshl_add_u64 v[198:199], s[2:3], 0, v[234:235]
	global_store_dwordx2 v[198:199], v[196:197], off
	s_and_saveexec_b64 s[4:5], vcc
	s_cbranch_execz .LBB0_1028
	s_waitcnt lgkmcnt(0)
	v_add_f32_e32 v195, v188, v189
	s_lshl_b32 s36, s30, 2
	v_lshlrev_b64 v[188:189], 7, v[184:185]
	s_ashr_i32 s37, s36, 31
	v_lshl_add_u64 v[188:189], s[10:11], 0, v[188:189]
	v_lshl_add_u64 v[188:189], s[36:37], 2, v[188:189]
	s_lshl_b32 s36, s45, 2
	s_mov_b32 s37, s13
	v_lshl_add_u64 v[188:189], v[188:189], 0, s[36:37]
	global_store_dword v[188:189], v195, off

.LBB0_1167:
	ds_read_b128 v[148:151], v143
	ds_read_b128 v[152:155], v143 offset:1024
	ds_read_b128 v[156:159], v143 offset:2048
	ds_read_b128 v[160:163], v143 offset:3072
	s_add_u32 s24, s22, 0xfff80080
	s_addc_u32 s25, s23, -1
	s_cmp_eq_u32 s53, 28
	s_cselect_b32 s27, s15, s25
	s_cselect_b32 s26, s49, s24
	s_cselect_b32 s25, s13, s52
	s_cselect_b32 s24, s50, s51

	s_add_i32 m0, s21, 0xc000
	ds_read_b128 v[164:167], v145
	ds_read_b128 v[176:179], v145 offset:1024
	ds_read_b128 v[180:183], v145 offset:2048
	ds_read_b128 v[184:187], v145 offset:3072
	ds_read_b128 v[188:191], v145 offset:4096
	ds_read_b128 v[192:195], v145 offset:5120
	ds_read_b128 v[196:199], v145 offset:6144

	global_load_lds_dwordx4 v128, s[22:23]
	s_add_i32 m0, s21, 0xe000
	ds_read_b128 v[200:203], v145 offset:7168

	global_load_lds_dwordx4 v130, s[22:23]
	s_waitcnt lgkmcnt(8)
	s_barrier
	s_waitcnt lgkmcnt(0)


	v_mfma_f32_16x16x32_bf16 v[124:127], v[148:151], v[164:167], v[124:127]
	v_mfma_f32_16x16x32_bf16 v[120:123], v[156:159], v[164:167], v[120:123]
	v_mfma_f32_16x16x32_bf16 v[116:119], v[148:151], v[180:183], v[116:119]
	v_mfma_f32_16x16x32_bf16 v[104:107], v[156:159], v[180:183], v[104:107]
	v_mfma_f32_16x16x32_bf16 v[96:99], v[148:151], v[188:191], v[96:99]
	v_mfma_f32_16x16x32_bf16 v[88:91], v[156:159], v[188:191], v[88:91]
	v_mfma_f32_16x16x32_bf16 v[80:83], v[148:151], v[196:199], v[80:83]
	v_mfma_f32_16x16x32_bf16 v[72:75], v[156:159], v[196:199], v[72:75]
	v_mfma_f32_16x16x32_bf16 v[124:127], v[152:155], v[176:179], v[124:127]
	v_mfma_f32_16x16x32_bf16 v[120:123], v[160:163], v[176:179], v[120:123]
	v_mfma_f32_16x16x32_bf16 v[116:119], v[152:155], v[184:187], v[116:119]
	v_mfma_f32_16x16x32_bf16 v[104:107], v[160:163], v[184:187], v[104:107]
	v_mfma_f32_16x16x32_bf16 v[96:99], v[152:155], v[192:195], v[96:99]
	v_mfma_f32_16x16x32_bf16 v[88:91], v[160:163], v[192:195], v[88:91]
	v_mfma_f32_16x16x32_bf16 v[80:83], v[152:155], v[200:203], v[80:83]
	v_mfma_f32_16x16x32_bf16 v[72:75], v[160:163], v[200:203], v[72:75]

	s_barrier
	s_add_i32 s54, s45, s31
	s_add_u32 s66, s24, s10
	s_addc_u32 s67, s25, s11
	s_mov_b32 m0, s54
	ds_read_b128 v[204:207], v147
	ds_read_b128 v[218:221], v147 offset:1024
	ds_read_b128 v[222:225], v147 offset:2048

	global_load_lds_dwordx4 v172, s[24:25]
	s_add_i32 m0, s54, 0x2000
	ds_read_b128 v[226:229], v147 offset:3072

	global_load_lds_dwordx4 v174, s[24:25]
	s_barrier
	s_waitcnt lgkmcnt(0)


	v_mfma_f32_16x16x32_bf16 v[112:115], v[204:207], v[164:167], v[112:115]
	v_mfma_f32_16x16x32_bf16 v[108:111], v[222:225], v[164:167], v[108:111]
	v_mfma_f32_16x16x32_bf16 v[100:103], v[204:207], v[180:183], v[100:103]
	v_mfma_f32_16x16x32_bf16 v[92:95], v[222:225], v[180:183], v[92:95]
	v_mfma_f32_16x16x32_bf16 v[84:87], v[204:207], v[188:191], v[84:87]
	v_mfma_f32_16x16x32_bf16 v[76:79], v[222:225], v[188:191], v[76:79]
	v_mfma_f32_16x16x32_bf16 v[68:71], v[204:207], v[196:199], v[68:71]
	v_mfma_f32_16x16x32_bf16 v[64:67], v[222:225], v[196:199], v[64:67]
	v_mfma_f32_16x16x32_bf16 v[112:115], v[218:221], v[176:179], v[112:115]
	v_mfma_f32_16x16x32_bf16 v[108:111], v[226:229], v[176:179], v[108:111]
	v_mfma_f32_16x16x32_bf16 v[100:103], v[218:221], v[184:187], v[100:103]
	v_mfma_f32_16x16x32_bf16 v[92:95], v[226:229], v[184:187], v[92:95]
	v_mfma_f32_16x16x32_bf16 v[84:87], v[218:221], v[192:195], v[84:87]
	v_mfma_f32_16x16x32_bf16 v[76:79], v[226:229], v[192:195], v[76:79]
	v_mfma_f32_16x16x32_bf16 v[68:71], v[218:221], v[200:203], v[68:71]
	v_mfma_f32_16x16x32_bf16 v[64:67], v[226:229], v[200:203], v[64:67]

	s_mov_b32 m0, s21
	s_add_u32 s68, s26, s10
	s_addc_u32 s69, s27, s11
	s_barrier
	ds_read_b128 v[164:167], v145 offset:16384
	ds_read_b128 v[176:179], v145 offset:17408
	ds_read_b128 v[180:183], v145 offset:18432
	ds_read_b128 v[184:187], v145 offset:19456
	ds_read_b128 v[188:191], v145 offset:20480
	ds_read_b128 v[192:195], v145 offset:21504
	ds_read_b128 v[196:199], v145 offset:22528

	global_load_lds_dwordx4 v172, s[26:27]
	s_mov_b32 m0, s35
	ds_read_b128 v[200:203], v145 offset:23552

	global_load_lds_dwordx4 v174, s[26:27]
	s_barrier
	s_waitcnt lgkmcnt(0)


	v_mfma_f32_16x16x32_bf16 v[60:63], v[148:151], v[164:167], v[60:63]
	v_mfma_f32_16x16x32_bf16 v[56:59], v[156:159], v[164:167], v[56:59]
	v_mfma_f32_16x16x32_bf16 v[48:51], v[148:151], v[180:183], v[48:51]
	v_mfma_f32_16x16x32_bf16 v[40:43], v[156:159], v[180:183], v[40:43]
	v_mfma_f32_16x16x32_bf16 v[32:35], v[148:151], v[188:191], v[32:35]
	v_mfma_f32_16x16x32_bf16 v[24:27], v[156:159], v[188:191], v[24:27]
	v_mfma_f32_16x16x32_bf16 v[16:19], v[148:151], v[196:199], v[16:19]
	v_mfma_f32_16x16x32_bf16 v[8:11], v[156:159], v[196:199], v[8:11]
	v_mfma_f32_16x16x32_bf16 v[60:63], v[152:155], v[176:179], v[60:63]
	v_mfma_f32_16x16x32_bf16 v[56:59], v[160:163], v[176:179], v[56:59]
	v_mfma_f32_16x16x32_bf16 v[48:51], v[152:155], v[184:187], v[48:51]
	v_mfma_f32_16x16x32_bf16 v[40:43], v[160:163], v[184:187], v[40:43]
	v_mfma_f32_16x16x32_bf16 v[32:35], v[152:155], v[192:195], v[32:35]
	v_mfma_f32_16x16x32_bf16 v[24:27], v[160:163], v[192:195], v[24:27]
	v_mfma_f32_16x16x32_bf16 v[16:19], v[152:155], v[200:203], v[16:19]
	v_mfma_f32_16x16x32_bf16 v[8:11], v[160:163], v[200:203], v[8:11]

	s_barrier
	s_add_i32 s56, s46, s31
	s_mov_b32 m0, s56
	s_add_u32 s54, s24, 0x80000
	s_addc_u32 s55, s25, 0


	global_load_lds_dwordx4 v172, s[54:55]
	s_add_i32 m0, s56, 0x2000
	s_nop 0

	global_load_lds_dwordx4 v174, s[54:55]
	s_waitcnt vmcnt(6)
	s_barrier

	v_mfma_f32_16x16x32_bf16 v[52:55], v[204:207], v[164:167], v[52:55]
	v_mfma_f32_16x16x32_bf16 v[44:47], v[222:225], v[164:167], v[44:47]
	v_mfma_f32_16x16x32_bf16 v[36:39], v[204:207], v[180:183], v[36:39]
	v_mfma_f32_16x16x32_bf16 v[28:31], v[222:225], v[180:183], v[28:31]
	v_mfma_f32_16x16x32_bf16 v[20:23], v[204:207], v[188:191], v[20:23]
	v_mfma_f32_16x16x32_bf16 v[12:15], v[222:225], v[188:191], v[12:15]
	v_mfma_f32_16x16x32_bf16 v[4:7], v[204:207], v[196:199], v[4:7]
	v_mfma_f32_16x16x32_bf16 v[0:3], v[222:225], v[196:199], v[0:3]
	v_mfma_f32_16x16x32_bf16 v[52:55], v[218:221], v[176:179], v[52:55]
	v_mfma_f32_16x16x32_bf16 v[44:47], v[226:229], v[176:179], v[44:47]
	v_mfma_f32_16x16x32_bf16 v[36:39], v[218:221], v[184:187], v[36:39]
	v_mfma_f32_16x16x32_bf16 v[28:31], v[226:229], v[184:187], v[28:31]
	v_mfma_f32_16x16x32_bf16 v[20:23], v[218:221], v[192:195], v[20:23]
	v_mfma_f32_16x16x32_bf16 v[12:15], v[226:229], v[192:195], v[12:15]
	v_mfma_f32_16x16x32_bf16 v[4:7], v[218:221], v[200:203], v[4:7]
	v_mfma_f32_16x16x32_bf16 v[0:3], v[226:229], v[200:203], v[0:3]

	s_add_i32 s54, 0, 0x18000

	s_barrier
	ds_read_b128 v[148:151], v143 offset:32768
	ds_read_b128 v[152:155], v143 offset:33792
	ds_read_b128 v[156:159], v143 offset:34816
	ds_read_b128 v[160:163], v143 offset:35840
	s_add_u32 s26, s26, 0x80000
	s_addc_u32 s27, s27, 0
	s_mov_b32 m0, s36

	ds_read_b128 v[164:167], v145 offset:32768
	ds_read_b128 v[176:179], v145 offset:33792
	ds_read_b128 v[180:183], v145 offset:34816
	ds_read_b128 v[184:187], v145 offset:35840
	ds_read_b128 v[188:191], v145 offset:36864
	ds_read_b128 v[192:195], v145 offset:37888
	ds_read_b128 v[196:199], v145 offset:38912

	global_load_lds_dwordx4 v172, s[26:27]
	s_mov_b32 m0, s37
	ds_read_b128 v[200:203], v145 offset:39936

	global_load_lds_dwordx4 v174, s[26:27]
	s_waitcnt lgkmcnt(8)
	s_barrier
	s_waitcnt lgkmcnt(0)


	v_mfma_f32_16x16x32_bf16 v[124:127], v[148:151], v[164:167], v[124:127]
	v_mfma_f32_16x16x32_bf16 v[120:123], v[156:159], v[164:167], v[120:123]
	v_mfma_f32_16x16x32_bf16 v[116:119], v[148:151], v[180:183], v[116:119]
	v_mfma_f32_16x16x32_bf16 v[104:107], v[156:159], v[180:183], v[104:107]
	v_mfma_f32_16x16x32_bf16 v[96:99], v[148:151], v[188:191], v[96:99]
	v_mfma_f32_16x16x32_bf16 v[88:91], v[156:159], v[188:191], v[88:91]
	v_mfma_f32_16x16x32_bf16 v[80:83], v[148:151], v[196:199], v[80:83]
	v_mfma_f32_16x16x32_bf16 v[72:75], v[156:159], v[196:199], v[72:75]
	v_mfma_f32_16x16x32_bf16 v[124:127], v[152:155], v[176:179], v[124:127]
	v_mfma_f32_16x16x32_bf16 v[120:123], v[160:163], v[176:179], v[120:123]
	v_mfma_f32_16x16x32_bf16 v[116:119], v[152:155], v[184:187], v[116:119]
	v_mfma_f32_16x16x32_bf16 v[104:107], v[160:163], v[184:187], v[104:107]
	v_mfma_f32_16x16x32_bf16 v[96:99], v[152:155], v[192:195], v[96:99]
	v_mfma_f32_16x16x32_bf16 v[88:91], v[160:163], v[192:195], v[88:91]
	v_mfma_f32_16x16x32_bf16 v[80:83], v[152:155], v[200:203], v[80:83]
	v_mfma_f32_16x16x32_bf16 v[72:75], v[160:163], v[200:203], v[72:75]

	s_barrier
	s_add_i32 s26, 0, 0x1c000
	s_add_i32 s27, s54, s31


	s_mov_b32 m0, s27
	ds_read_b128 v[204:207], v147 offset:32768
	ds_read_b128 v[218:221], v147 offset:33792
	ds_read_b128 v[222:225], v147 offset:34816

	global_load_lds_dwordx4 v172, s[66:67]
	s_add_i32 m0, s27, 0x2000
	ds_read_b128 v[226:229], v147 offset:35840

	global_load_lds_dwordx4 v174, s[66:67]
	s_barrier
	s_waitcnt lgkmcnt(0)


	v_mfma_f32_16x16x32_bf16 v[112:115], v[204:207], v[164:167], v[112:115]
	v_mfma_f32_16x16x32_bf16 v[108:111], v[222:225], v[164:167], v[108:111]
	v_mfma_f32_16x16x32_bf16 v[100:103], v[204:207], v[180:183], v[100:103]
	v_mfma_f32_16x16x32_bf16 v[92:95], v[222:225], v[180:183], v[92:95]
	v_mfma_f32_16x16x32_bf16 v[84:87], v[204:207], v[188:191], v[84:87]
	v_mfma_f32_16x16x32_bf16 v[76:79], v[222:225], v[188:191], v[76:79]
	v_mfma_f32_16x16x32_bf16 v[68:71], v[204:207], v[196:199], v[68:71]
	v_mfma_f32_16x16x32_bf16 v[64:67], v[222:225], v[196:199], v[64:67]
	v_mfma_f32_16x16x32_bf16 v[112:115], v[218:221], v[176:179], v[112:115]
	v_mfma_f32_16x16x32_bf16 v[108:111], v[226:229], v[176:179], v[108:111]
	v_mfma_f32_16x16x32_bf16 v[100:103], v[218:221], v[184:187], v[100:103]
	v_mfma_f32_16x16x32_bf16 v[92:95], v[226:229], v[184:187], v[92:95]
	v_mfma_f32_16x16x32_bf16 v[84:87], v[218:221], v[192:195], v[84:87]
	v_mfma_f32_16x16x32_bf16 v[76:79], v[226:229], v[192:195], v[76:79]
	v_mfma_f32_16x16x32_bf16 v[68:71], v[218:221], v[200:203], v[68:71]
	v_mfma_f32_16x16x32_bf16 v[64:67], v[226:229], v[200:203], v[64:67]

	s_mov_b32 m0, s41

	s_barrier
	ds_read_b128 v[164:167], v145 offset:49152
	ds_read_b128 v[176:179], v145 offset:50176
	ds_read_b128 v[180:183], v145 offset:51200
	ds_read_b128 v[184:187], v145 offset:52224
	ds_read_b128 v[188:191], v145 offset:53248
	ds_read_b128 v[192:195], v145 offset:54272
	ds_read_b128 v[196:199], v145 offset:55296

	global_load_lds_dwordx4 v172, s[68:69]
	s_mov_b32 m0, s42
	ds_read_b128 v[200:203], v145 offset:56320

	global_load_lds_dwordx4 v174, s[68:69]
	s_barrier
	s_waitcnt lgkmcnt(0)


	v_mfma_f32_16x16x32_bf16 v[60:63], v[148:151], v[164:167], v[60:63]
	v_mfma_f32_16x16x32_bf16 v[56:59], v[156:159], v[164:167], v[56:59]
	v_mfma_f32_16x16x32_bf16 v[48:51], v[148:151], v[180:183], v[48:51]
	v_mfma_f32_16x16x32_bf16 v[40:43], v[156:159], v[180:183], v[40:43]
	v_mfma_f32_16x16x32_bf16 v[32:35], v[148:151], v[188:191], v[32:35]
	v_mfma_f32_16x16x32_bf16 v[24:27], v[156:159], v[188:191], v[24:27]
	v_mfma_f32_16x16x32_bf16 v[16:19], v[148:151], v[196:199], v[16:19]
	v_mfma_f32_16x16x32_bf16 v[8:11], v[156:159], v[196:199], v[8:11]
	v_mfma_f32_16x16x32_bf16 v[60:63], v[152:155], v[176:179], v[60:63]
	v_mfma_f32_16x16x32_bf16 v[56:59], v[160:163], v[176:179], v[56:59]
	v_mfma_f32_16x16x32_bf16 v[48:51], v[152:155], v[184:187], v[48:51]
	v_mfma_f32_16x16x32_bf16 v[40:43], v[160:163], v[184:187], v[40:43]
	v_mfma_f32_16x16x32_bf16 v[32:35], v[152:155], v[192:195], v[32:35]
	v_mfma_f32_16x16x32_bf16 v[24:27], v[160:163], v[192:195], v[24:27]
	v_mfma_f32_16x16x32_bf16 v[16:19], v[152:155], v[200:203], v[16:19]
	v_mfma_f32_16x16x32_bf16 v[8:11], v[160:163], v[200:203], v[8:11]

	s_barrier
	s_add_u32 s24, s24, 0x80080
	s_addc_u32 s25, s25, 0
	s_add_i32 s26, s26, s31
	s_mov_b32 m0, s26
	s_add_i32 s53, s53, 2

	global_load_lds_dwordx4 v172, s[24:25]
	s_add_i32 m0, s26, 0x2000
	s_add_u32 s22, s22, 0x100
	s_addc_u32 s23, s23, 0

	global_load_lds_dwordx4 v174, s[24:25]
	s_add_u32 s51, s51, 0x100
	s_addc_u32 s52, s52, 0
	s_waitcnt vmcnt(6)
	s_barrier

	v_mfma_f32_16x16x32_bf16 v[52:55], v[204:207], v[164:167], v[52:55]
	v_mfma_f32_16x16x32_bf16 v[44:47], v[222:225], v[164:167], v[44:47]
	v_mfma_f32_16x16x32_bf16 v[36:39], v[204:207], v[180:183], v[36:39]
	v_mfma_f32_16x16x32_bf16 v[28:31], v[222:225], v[180:183], v[28:31]
	v_mfma_f32_16x16x32_bf16 v[20:23], v[204:207], v[188:191], v[20:23]
	v_mfma_f32_16x16x32_bf16 v[12:15], v[222:225], v[188:191], v[12:15]
	v_mfma_f32_16x16x32_bf16 v[4:7], v[204:207], v[196:199], v[4:7]
	v_mfma_f32_16x16x32_bf16 v[0:3], v[222:225], v[196:199], v[0:3]
	v_mfma_f32_16x16x32_bf16 v[52:55], v[218:221], v[176:179], v[52:55]
	v_mfma_f32_16x16x32_bf16 v[44:47], v[226:229], v[176:179], v[44:47]
	v_mfma_f32_16x16x32_bf16 v[36:39], v[218:221], v[184:187], v[36:39]
	v_mfma_f32_16x16x32_bf16 v[28:31], v[226:229], v[184:187], v[28:31]
	v_mfma_f32_16x16x32_bf16 v[20:23], v[218:221], v[192:195], v[20:23]
	v_mfma_f32_16x16x32_bf16 v[12:15], v[226:229], v[192:195], v[12:15]
	v_mfma_f32_16x16x32_bf16 v[4:7], v[218:221], v[200:203], v[4:7]
	v_mfma_f32_16x16x32_bf16 v[0:3], v[226:229], v[200:203], v[0:3]


	s_cmp_gt_u32 s53, 29
	s_barrier
	s_cbranch_scc0 .LBB0_1167
	s_lshl_b32 s13, s20, 8
	v_mov_b32_e32 v138, v210
	v_mov_b32_e32 v142, v169
	s_add_i32 s13, s13, s39
	s_lshl_b32 s15, s48, 7
	v_add_u32_e32 v136, s13, v142
	v_ashrrev_i32_e32 v137, 31, v136
	v_lshl_add_u64 v[140:141], v[136:137], 2, s[2:3]
	global_load_dword v154, v[140:141], off
	global_load_dword v152, v[140:141], off offset:64
	v_lshl_add_u32 v138, v138, 4, v142
	v_and_b32_e32 v142, 3, v142
	v_ashrrev_i32_e32 v144, 2, v138
	v_and_b32_e32 v138, -4, v138
	v_lshl_or_b32 v146, v142, 2, s15
	v_add_u32_e32 v151, s13, v144
	v_lshl_add_u32 v149, v142, 6, v138
	v_or_b32_e32 v156, s40, v146
	global_load_dword v150, v[140:141], off offset:128
	global_load_dword v148, v[140:141], off offset:192
	global_load_dword v146, v[140:141], off offset:512
	global_load_dword v144, v[140:141], off offset:576
	global_load_dword v142, v[140:141], off offset:640
	global_load_dword v138, v[140:141], off offset:704
	v_mov_b64_e32 v[136:137], s[0:1]
	v_ashrrev_i32_e32 v157, 31, v156
	v_mad_i64_i32 v[158:159], s[22:23], v151, s47, v[136:137]
	v_lshlrev_b64 v[140:141], 1, v[156:157]
	v_lshl_add_u64 v[156:157], v[158:159], 0, v[140:141]
	v_add_u32_e32 v153, 16, v151
	s_and_b64 vcc, exec, s[4:5]
	s_mov_b32 s48, s12
	s_mov_b32 s20, s14
	s_mov_b64 s[24:25], s[18:19]
	s_waitcnt vmcnt(0)
	v_pk_mul_f32 v[126:127], v[126:127], v[154:155] op_sel_hi:[1,0]
	v_pk_mul_f32 v[124:125], v[124:125], v[154:155] op_sel_hi:[1,0]
	v_pk_mul_f32 v[114:115], v[114:115], v[154:155] op_sel_hi:[1,0]
	v_pk_mul_f32 v[112:113], v[112:113], v[154:155] op_sel_hi:[1,0]
	v_pk_mul_f32 v[122:123], v[122:123], v[154:155] op_sel_hi:[1,0]
	v_pk_mul_f32 v[120:121], v[120:121], v[154:155] op_sel_hi:[1,0]
	v_pk_mul_f32 v[110:111], v[110:111], v[154:155] op_sel_hi:[1,0]
	v_pk_mul_f32 v[108:109], v[108:109], v[154:155] op_sel_hi:[1,0]
	v_mul_f32_e32 v154, 0xbfb8aa3b, v124
	v_mul_f32_e32 v155, 0xbfb8aa3b, v125
	v_mul_f32_e32 v158, 0xbfb8aa3b, v126
	v_mul_f32_e32 v159, 0xbfb8aa3b, v127
	v_mul_f32_e32 v160, 0xbfb8aa3b, v120
	v_mul_f32_e32 v161, 0xbfb8aa3b, v121
	v_mul_f32_e32 v162, 0xbfb8aa3b, v122
	v_mul_f32_e32 v163, 0xbfb8aa3b, v123
	v_exp_f32_e32 v154, v154
	v_exp_f32_e32 v155, v155
	v_exp_f32_e32 v158, v158
	v_exp_f32_e32 v159, v159
	v_exp_f32_e32 v160, v160
	v_exp_f32_e32 v161, v161
	v_exp_f32_e32 v162, v162
	v_exp_f32_e32 v163, v163
	v_add_f32_e32 v154, 1.0, v154
	v_add_f32_e32 v155, 1.0, v155
	v_add_f32_e32 v158, 1.0, v158
	v_add_f32_e32 v159, 1.0, v159
	v_add_f32_e32 v160, 1.0, v160
	v_add_f32_e32 v161, 1.0, v161
	v_add_f32_e32 v162, 1.0, v162
	v_add_f32_e32 v163, 1.0, v163
	v_rcp_f32_e32 v154, v154
	v_rcp_f32_e32 v155, v155
	v_rcp_f32_e32 v158, v158
	v_rcp_f32_e32 v159, v159
	v_rcp_f32_e32 v160, v160
	v_rcp_f32_e32 v161, v161
	v_rcp_f32_e32 v162, v162
	v_rcp_f32_e32 v163, v163
	v_pk_mul_f32 v[124:125], v[124:125], v[154:155]
	v_pk_mul_f32 v[126:127], v[126:127], v[158:159]
	v_pk_mul_f32 v[120:121], v[120:121], v[160:161]
	v_pk_mul_f32 v[122:123], v[122:123], v[162:163]
	v_pk_mul_f32 v[112:113], v[112:113], v[124:125]
	v_pk_mul_f32 v[114:115], v[114:115], v[126:127]
	v_pk_mul_f32 v[118:119], v[118:119], v[152:153] op_sel_hi:[1,0]
	v_pk_mul_f32 v[116:117], v[116:117], v[152:153] op_sel_hi:[1,0]
	v_pk_mul_f32 v[108:109], v[108:109], v[120:121]
	v_pk_mul_f32 v[110:111], v[110:111], v[122:123]
	v_cvt_pk_bf16_f32 v112, v112, v113
	v_cvt_pk_bf16_f32 v113, v114, v115
	v_mul_f32_e32 v164, 0xbfb8aa3b, v116
	v_mul_f32_e32 v165, 0xbfb8aa3b, v117
	v_mul_f32_e32 v166, 0xbfb8aa3b, v118
	v_mul_f32_e32 v167, 0xbfb8aa3b, v119
	v_cvt_pk_bf16_f32 v114, v108, v109
	v_cvt_pk_bf16_f32 v111, v110, v111
	ds_bpermute_b32 v108, v149, v112
	ds_bpermute_b32 v109, v149, v113
	v_exp_f32_e32 v164, v164
	v_exp_f32_e32 v165, v165
	v_exp_f32_e32 v166, v166
	v_exp_f32_e32 v167, v167
	ds_bpermute_b32 v110, v149, v114
	ds_bpermute_b32 v111, v149, v111
	v_add_f32_e32 v164, 1.0, v164
	v_add_f32_e32 v113, 1.0, v165
	s_waitcnt lgkmcnt(0)
	global_store_dwordx2 v[156:157], v[108:109], off
	global_store_dwordx2 v[156:157], v[110:111], off offset:32
	v_add_f32_e32 v108, 1.0, v166
	v_add_f32_e32 v109, 1.0, v167
	v_rcp_f32_e32 v112, v164
	v_rcp_f32_e32 v113, v113
	v_rcp_f32_e32 v108, v108
	v_rcp_f32_e32 v109, v109
	v_pk_mul_f32 v[102:103], v[102:103], v[152:153] op_sel_hi:[1,0]
	v_pk_mul_f32 v[100:101], v[100:101], v[152:153] op_sel_hi:[1,0]
	v_pk_mul_f32 v[110:111], v[116:117], v[112:113]
	v_pk_mul_f32 v[108:109], v[118:119], v[108:109]
	v_pk_mul_f32 v[100:101], v[100:101], v[110:111]
	v_pk_mul_f32 v[102:103], v[102:103], v[108:109]
	v_cvt_pk_bf16_f32 v100, v100, v101
	v_cvt_pk_bf16_f32 v101, v102, v103
	v_pk_mul_f32 v[102:103], v[106:107], v[152:153] op_sel_hi:[1,0]
	v_pk_mul_f32 v[104:105], v[104:105], v[152:153] op_sel_hi:[1,0]
	v_mul_f32_e32 v108, 0xbfb8aa3b, v102
	v_mul_f32_e32 v106, 0xbfb8aa3b, v104
	v_mul_f32_e32 v107, 0xbfb8aa3b, v105
	v_mul_f32_e32 v109, 0xbfb8aa3b, v103
	v_exp_f32_e32 v106, v106
	v_exp_f32_e32 v107, v107
	v_exp_f32_e32 v108, v108
	v_exp_f32_e32 v109, v109
	v_add_f32_e32 v106, 1.0, v106
	v_add_f32_e32 v107, 1.0, v107
	v_add_f32_e32 v108, 1.0, v108
	v_add_f32_e32 v109, 1.0, v109
	v_rcp_f32_e32 v106, v106
	v_rcp_f32_e32 v107, v107
	v_rcp_f32_e32 v108, v108
	v_rcp_f32_e32 v109, v109
	v_pk_mul_f32 v[94:95], v[94:95], v[152:153] op_sel_hi:[1,0]
	v_pk_mul_f32 v[92:93], v[92:93], v[152:153] op_sel_hi:[1,0]
	v_pk_mul_f32 v[104:105], v[104:105], v[106:107]
	v_pk_mul_f32 v[102:103], v[102:103], v[108:109]
	v_pk_mul_f32 v[92:93], v[92:93], v[104:105]
	v_pk_mul_f32 v[94:95], v[94:95], v[102:103]
	ds_bpermute_b32 v100, v149, v100
	ds_bpermute_b32 v101, v149, v101
	v_cvt_pk_bf16_f32 v92, v92, v93
	v_cvt_pk_bf16_f32 v93, v94, v95
	ds_bpermute_b32 v92, v149, v92
	ds_bpermute_b32 v93, v149, v93
	v_mad_i64_i32 v[94:95], s[22:23], v153, s47, v[136:137]
	v_lshl_add_u64 v[94:95], v[94:95], 0, v[140:141]
	s_waitcnt lgkmcnt(2)
	global_store_dwordx2 v[94:95], v[100:101], off
	s_waitcnt lgkmcnt(0)
	global_store_dwordx2 v[94:95], v[92:93], off offset:32
	v_pk_mul_f32 v[92:93], v[98:99], v[150:151] op_sel_hi:[1,0]
	v_pk_mul_f32 v[94:95], v[96:97], v[150:151] op_sel_hi:[1,0]
	v_mul_f32_e32 v98, 0xbfb8aa3b, v92
	v_mul_f32_e32 v96, 0xbfb8aa3b, v94
	v_mul_f32_e32 v97, 0xbfb8aa3b, v95
	v_mul_f32_e32 v99, 0xbfb8aa3b, v93
	v_exp_f32_e32 v96, v96
	v_exp_f32_e32 v97, v97
	v_exp_f32_e32 v98, v98
	v_exp_f32_e32 v99, v99
	v_add_f32_e32 v96, 1.0, v96
	v_add_f32_e32 v97, 1.0, v97
	v_add_f32_e32 v98, 1.0, v98
	v_add_f32_e32 v99, 1.0, v99
	v_rcp_f32_e32 v96, v96
	v_rcp_f32_e32 v97, v97
	v_rcp_f32_e32 v98, v98
	v_rcp_f32_e32 v99, v99
	v_pk_mul_f32 v[86:87], v[86:87], v[150:151] op_sel_hi:[1,0]
	v_pk_mul_f32 v[84:85], v[84:85], v[150:151] op_sel_hi:[1,0]
	v_pk_mul_f32 v[94:95], v[94:95], v[96:97]
	v_pk_mul_f32 v[92:93], v[92:93], v[98:99]
	v_pk_mul_f32 v[84:85], v[84:85], v[94:95]
	v_pk_mul_f32 v[86:87], v[86:87], v[92:93]
	v_cvt_pk_bf16_f32 v84, v84, v85
	v_cvt_pk_bf16_f32 v85, v86, v87
	v_pk_mul_f32 v[86:87], v[90:91], v[150:151] op_sel_hi:[1,0]
	v_pk_mul_f32 v[88:89], v[88:89], v[150:151] op_sel_hi:[1,0]
	v_mul_f32_e32 v92, 0xbfb8aa3b, v86
	v_mul_f32_e32 v90, 0xbfb8aa3b, v88
	v_mul_f32_e32 v91, 0xbfb8aa3b, v89
	v_mul_f32_e32 v93, 0xbfb8aa3b, v87
	v_exp_f32_e32 v90, v90
	v_exp_f32_e32 v91, v91
	v_exp_f32_e32 v92, v92
	v_exp_f32_e32 v93, v93
	v_add_f32_e32 v90, 1.0, v90
	v_add_f32_e32 v91, 1.0, v91
	v_add_f32_e32 v92, 1.0, v92
	v_add_f32_e32 v93, 1.0, v93
	v_rcp_f32_e32 v90, v90
	v_rcp_f32_e32 v91, v91
	v_rcp_f32_e32 v92, v92
	v_rcp_f32_e32 v93, v93
	v_pk_mul_f32 v[78:79], v[78:79], v[150:151] op_sel_hi:[1,0]
	v_pk_mul_f32 v[76:77], v[76:77], v[150:151] op_sel_hi:[1,0]
	v_pk_mul_f32 v[88:89], v[88:89], v[90:91]
	v_pk_mul_f32 v[86:87], v[86:87], v[92:93]
	v_pk_mul_f32 v[76:77], v[76:77], v[88:89]
	v_pk_mul_f32 v[78:79], v[78:79], v[86:87]
	ds_bpermute_b32 v84, v149, v84
	ds_bpermute_b32 v85, v149, v85
	v_cvt_pk_bf16_f32 v76, v76, v77
	v_cvt_pk_bf16_f32 v77, v78, v79
	ds_bpermute_b32 v76, v149, v76
	ds_bpermute_b32 v77, v149, v77
	v_add_u32_e32 v100, 32, v151
	v_mad_i64_i32 v[78:79], s[22:23], v100, s47, v[136:137]
	v_lshl_add_u64 v[78:79], v[78:79], 0, v[140:141]
	s_waitcnt lgkmcnt(2)
	global_store_dwordx2 v[78:79], v[84:85], off
	s_waitcnt lgkmcnt(0)
	global_store_dwordx2 v[78:79], v[76:77], off offset:32
	v_pk_mul_f32 v[76:77], v[82:83], v[148:149] op_sel_hi:[1,0]
	v_pk_mul_f32 v[78:79], v[80:81], v[148:149] op_sel_hi:[1,0]
	v_mul_f32_e32 v82, 0xbfb8aa3b, v76
	v_mul_f32_e32 v80, 0xbfb8aa3b, v78
	v_mul_f32_e32 v81, 0xbfb8aa3b, v79
	v_mul_f32_e32 v83, 0xbfb8aa3b, v77
	v_exp_f32_e32 v80, v80
	v_exp_f32_e32 v81, v81
	v_exp_f32_e32 v82, v82
	v_exp_f32_e32 v83, v83
	v_add_f32_e32 v80, 1.0, v80
	v_add_f32_e32 v81, 1.0, v81
	v_add_f32_e32 v82, 1.0, v82
	v_add_f32_e32 v83, 1.0, v83
	v_rcp_f32_e32 v80, v80
	v_rcp_f32_e32 v81, v81
	v_rcp_f32_e32 v82, v82
	v_rcp_f32_e32 v83, v83
	v_pk_mul_f32 v[70:71], v[70:71], v[148:149] op_sel_hi:[1,0]
	v_pk_mul_f32 v[68:69], v[68:69], v[148:149] op_sel_hi:[1,0]
	v_pk_mul_f32 v[78:79], v[78:79], v[80:81]
	v_pk_mul_f32 v[76:77], v[76:77], v[82:83]
	v_pk_mul_f32 v[68:69], v[68:69], v[78:79]
	v_pk_mul_f32 v[70:71], v[70:71], v[76:77]
	v_cvt_pk_bf16_f32 v68, v68, v69
	v_cvt_pk_bf16_f32 v69, v70, v71
	v_pk_mul_f32 v[70:71], v[74:75], v[148:149] op_sel_hi:[1,0]
	v_pk_mul_f32 v[72:73], v[72:73], v[148:149] op_sel_hi:[1,0]
	v_mul_f32_e32 v76, 0xbfb8aa3b, v70
	v_mul_f32_e32 v74, 0xbfb8aa3b, v72
	v_mul_f32_e32 v75, 0xbfb8aa3b, v73
	v_mul_f32_e32 v77, 0xbfb8aa3b, v71
	v_exp_f32_e32 v74, v74
	v_exp_f32_e32 v75, v75
	v_exp_f32_e32 v76, v76
	v_exp_f32_e32 v77, v77
	v_add_f32_e32 v74, 1.0, v74
	v_add_f32_e32 v75, 1.0, v75
	v_add_f32_e32 v76, 1.0, v76
	v_add_f32_e32 v77, 1.0, v77
	v_rcp_f32_e32 v74, v74
	v_rcp_f32_e32 v75, v75
	v_rcp_f32_e32 v76, v76
	v_rcp_f32_e32 v77, v77
	v_pk_mul_f32 v[66:67], v[66:67], v[148:149] op_sel_hi:[1,0]
	v_pk_mul_f32 v[64:65], v[64:65], v[148:149] op_sel_hi:[1,0]
	v_pk_mul_f32 v[72:73], v[72:73], v[74:75]
	v_pk_mul_f32 v[70:71], v[70:71], v[76:77]
	v_pk_mul_f32 v[64:65], v[64:65], v[72:73]
	v_pk_mul_f32 v[66:67], v[66:67], v[70:71]
	ds_bpermute_b32 v68, v149, v68
	ds_bpermute_b32 v69, v149, v69
	v_cvt_pk_bf16_f32 v64, v64, v65
	v_cvt_pk_bf16_f32 v65, v66, v67
	ds_bpermute_b32 v64, v149, v64
	ds_bpermute_b32 v65, v149, v65
	v_add_u32_e32 v84, 48, v151
	v_mad_i64_i32 v[66:67], s[22:23], v84, s47, v[136:137]
	v_lshl_add_u64 v[66:67], v[66:67], 0, v[140:141]
	v_pk_mul_f32 v[60:61], v[60:61], v[146:147] op_sel_hi:[1,0]
	s_waitcnt lgkmcnt(2)
	global_store_dwordx2 v[66:67], v[68:69], off
	s_waitcnt lgkmcnt(0)
	global_store_dwordx2 v[66:67], v[64:65], off offset:32
	v_pk_mul_f32 v[62:63], v[62:63], v[146:147] op_sel_hi:[1,0]
	v_mul_f32_e32 v64, 0xbfb8aa3b, v60
	v_mul_f32_e32 v65, 0xbfb8aa3b, v61
	v_exp_f32_e32 v64, v64
	v_exp_f32_e32 v65, v65
	v_mul_f32_e32 v66, 0xbfb8aa3b, v62
	v_mul_f32_e32 v67, 0xbfb8aa3b, v63
	v_exp_f32_e32 v66, v66
	v_exp_f32_e32 v67, v67
	v_add_f32_e32 v64, 1.0, v64
	v_add_f32_e32 v65, 1.0, v65
	v_rcp_f32_e32 v64, v64
	v_rcp_f32_e32 v65, v65
	v_add_f32_e32 v66, 1.0, v66
	v_add_f32_e32 v67, 1.0, v67
	v_rcp_f32_e32 v66, v66
	v_rcp_f32_e32 v67, v67
	v_pk_mul_f32 v[52:53], v[52:53], v[146:147] op_sel_hi:[1,0]
	v_pk_mul_f32 v[60:61], v[60:61], v[64:65]
	v_pk_mul_f32 v[54:55], v[54:55], v[146:147] op_sel_hi:[1,0]
	v_pk_mul_f32 v[52:53], v[52:53], v[60:61]
	v_pk_mul_f32 v[60:61], v[62:63], v[66:67]
	v_cvt_pk_bf16_f32 v52, v52, v53
	v_pk_mul_f32 v[54:55], v[54:55], v[60:61]
	v_pk_mul_f32 v[56:57], v[56:57], v[146:147] op_sel_hi:[1,0]
	v_cvt_pk_bf16_f32 v53, v54, v55
	v_pk_mul_f32 v[54:55], v[58:59], v[146:147] op_sel_hi:[1,0]
	v_mul_f32_e32 v58, 0xbfb8aa3b, v56
	v_mul_f32_e32 v59, 0xbfb8aa3b, v57
	v_mul_f32_e32 v60, 0xbfb8aa3b, v54
	v_mul_f32_e32 v61, 0xbfb8aa3b, v55
	v_exp_f32_e32 v58, v58
	v_exp_f32_e32 v59, v59
	v_exp_f32_e32 v60, v60
	v_exp_f32_e32 v61, v61
	v_add_f32_e32 v58, 1.0, v58
	v_add_f32_e32 v59, 1.0, v59
	v_add_f32_e32 v60, 1.0, v60
	v_add_f32_e32 v61, 1.0, v61
	v_rcp_f32_e32 v58, v58
	v_rcp_f32_e32 v59, v59
	v_rcp_f32_e32 v60, v60
	v_rcp_f32_e32 v61, v61
	v_pk_mul_f32 v[46:47], v[46:47], v[146:147] op_sel_hi:[1,0]
	v_pk_mul_f32 v[44:45], v[44:45], v[146:147] op_sel_hi:[1,0]
	v_pk_mul_f32 v[56:57], v[56:57], v[58:59]
	v_pk_mul_f32 v[54:55], v[54:55], v[60:61]
	v_pk_mul_f32 v[44:45], v[44:45], v[56:57]
	v_pk_mul_f32 v[46:47], v[46:47], v[54:55]
	ds_bpermute_b32 v52, v149, v52
	ds_bpermute_b32 v53, v149, v53
	v_cvt_pk_bf16_f32 v44, v44, v45
	v_cvt_pk_bf16_f32 v45, v46, v47
	ds_bpermute_b32 v44, v149, v44
	ds_bpermute_b32 v45, v149, v45
	v_add_u32_e32 v68, 0x80, v151
	v_mad_i64_i32 v[46:47], s[22:23], v68, s47, v[136:137]
	v_lshl_add_u64 v[46:47], v[46:47], 0, v[140:141]
	s_waitcnt lgkmcnt(2)
	global_store_dwordx2 v[46:47], v[52:53], off
	s_waitcnt lgkmcnt(0)
	global_store_dwordx2 v[46:47], v[44:45], off offset:32
	v_pk_mul_f32 v[44:45], v[50:51], v[144:145] op_sel_hi:[1,0]
	v_pk_mul_f32 v[46:47], v[48:49], v[144:145] op_sel_hi:[1,0]
	v_mul_f32_e32 v50, 0xbfb8aa3b, v44
	v_mul_f32_e32 v48, 0xbfb8aa3b, v46
	v_mul_f32_e32 v49, 0xbfb8aa3b, v47
	v_mul_f32_e32 v51, 0xbfb8aa3b, v45
	v_exp_f32_e32 v48, v48
	v_exp_f32_e32 v49, v49
	v_exp_f32_e32 v50, v50
	v_exp_f32_e32 v51, v51
	v_add_f32_e32 v48, 1.0, v48
	v_add_f32_e32 v49, 1.0, v49
	v_add_f32_e32 v50, 1.0, v50
	v_add_f32_e32 v51, 1.0, v51
	v_rcp_f32_e32 v48, v48
	v_rcp_f32_e32 v49, v49
	v_rcp_f32_e32 v50, v50
	v_rcp_f32_e32 v51, v51
	v_pk_mul_f32 v[38:39], v[38:39], v[144:145] op_sel_hi:[1,0]
	v_pk_mul_f32 v[36:37], v[36:37], v[144:145] op_sel_hi:[1,0]
	v_pk_mul_f32 v[46:47], v[46:47], v[48:49]
	v_pk_mul_f32 v[44:45], v[44:45], v[50:51]
	v_pk_mul_f32 v[36:37], v[36:37], v[46:47]
	v_pk_mul_f32 v[38:39], v[38:39], v[44:45]
	v_cvt_pk_bf16_f32 v36, v36, v37
	v_cvt_pk_bf16_f32 v37, v38, v39
	v_pk_mul_f32 v[38:39], v[42:43], v[144:145] op_sel_hi:[1,0]
	v_pk_mul_f32 v[40:41], v[40:41], v[144:145] op_sel_hi:[1,0]
	v_mul_f32_e32 v44, 0xbfb8aa3b, v38
	v_mul_f32_e32 v42, 0xbfb8aa3b, v40
	v_mul_f32_e32 v43, 0xbfb8aa3b, v41
	v_mul_f32_e32 v45, 0xbfb8aa3b, v39
	v_exp_f32_e32 v42, v42
	v_exp_f32_e32 v43, v43
	v_exp_f32_e32 v44, v44
	v_exp_f32_e32 v45, v45
	v_add_f32_e32 v42, 1.0, v42
	v_add_f32_e32 v43, 1.0, v43
	v_add_f32_e32 v44, 1.0, v44
	v_add_f32_e32 v45, 1.0, v45
	v_rcp_f32_e32 v42, v42
	v_rcp_f32_e32 v43, v43
	v_rcp_f32_e32 v44, v44
	v_rcp_f32_e32 v45, v45
	v_pk_mul_f32 v[30:31], v[30:31], v[144:145] op_sel_hi:[1,0]
	v_pk_mul_f32 v[28:29], v[28:29], v[144:145] op_sel_hi:[1,0]
	v_pk_mul_f32 v[40:41], v[40:41], v[42:43]
	v_pk_mul_f32 v[38:39], v[38:39], v[44:45]
	v_pk_mul_f32 v[28:29], v[28:29], v[40:41]
	v_pk_mul_f32 v[30:31], v[30:31], v[38:39]
	ds_bpermute_b32 v36, v149, v36
	ds_bpermute_b32 v37, v149, v37
	v_cvt_pk_bf16_f32 v28, v28, v29
	v_cvt_pk_bf16_f32 v29, v30, v31
	ds_bpermute_b32 v28, v149, v28
	ds_bpermute_b32 v29, v149, v29
	v_add_u32_e32 v52, 0x90, v151
	v_mad_i64_i32 v[30:31], s[22:23], v52, s47, v[136:137]
	v_lshl_add_u64 v[30:31], v[30:31], 0, v[140:141]
	s_waitcnt lgkmcnt(2)
	global_store_dwordx2 v[30:31], v[36:37], off
	s_waitcnt lgkmcnt(0)
	global_store_dwordx2 v[30:31], v[28:29], off offset:32
	v_pk_mul_f32 v[28:29], v[34:35], v[142:143] op_sel_hi:[1,0]
	v_pk_mul_f32 v[30:31], v[32:33], v[142:143] op_sel_hi:[1,0]
	v_mul_f32_e32 v34, 0xbfb8aa3b, v28
	v_mul_f32_e32 v32, 0xbfb8aa3b, v30
	v_mul_f32_e32 v33, 0xbfb8aa3b, v31
	v_mul_f32_e32 v35, 0xbfb8aa3b, v29
	v_exp_f32_e32 v32, v32
	v_exp_f32_e32 v33, v33
	v_exp_f32_e32 v34, v34
	v_exp_f32_e32 v35, v35
	v_add_f32_e32 v32, 1.0, v32
	v_add_f32_e32 v33, 1.0, v33
	v_add_f32_e32 v34, 1.0, v34
	v_add_f32_e32 v35, 1.0, v35
	v_rcp_f32_e32 v32, v32
	v_rcp_f32_e32 v33, v33
	v_rcp_f32_e32 v34, v34
	v_rcp_f32_e32 v35, v35
	v_pk_mul_f32 v[22:23], v[22:23], v[142:143] op_sel_hi:[1,0]
	v_pk_mul_f32 v[20:21], v[20:21], v[142:143] op_sel_hi:[1,0]
	v_pk_mul_f32 v[30:31], v[30:31], v[32:33]
	v_pk_mul_f32 v[28:29], v[28:29], v[34:35]
	v_pk_mul_f32 v[20:21], v[20:21], v[30:31]
	v_pk_mul_f32 v[22:23], v[22:23], v[28:29]
	v_cvt_pk_bf16_f32 v20, v20, v21
	v_cvt_pk_bf16_f32 v21, v22, v23
	v_pk_mul_f32 v[22:23], v[26:27], v[142:143] op_sel_hi:[1,0]
	v_pk_mul_f32 v[24:25], v[24:25], v[142:143] op_sel_hi:[1,0]
	v_mul_f32_e32 v28, 0xbfb8aa3b, v22
	v_mul_f32_e32 v26, 0xbfb8aa3b, v24
	v_mul_f32_e32 v27, 0xbfb8aa3b, v25
	v_mul_f32_e32 v29, 0xbfb8aa3b, v23
	v_exp_f32_e32 v26, v26
	v_exp_f32_e32 v27, v27
	v_exp_f32_e32 v28, v28
	v_exp_f32_e32 v29, v29
	v_add_f32_e32 v26, 1.0, v26
	v_add_f32_e32 v27, 1.0, v27
	v_add_f32_e32 v28, 1.0, v28
	v_add_f32_e32 v29, 1.0, v29
	v_rcp_f32_e32 v26, v26
	v_rcp_f32_e32 v27, v27
	v_rcp_f32_e32 v28, v28
	v_rcp_f32_e32 v29, v29
	v_pk_mul_f32 v[14:15], v[14:15], v[142:143] op_sel_hi:[1,0]
	v_pk_mul_f32 v[12:13], v[12:13], v[142:143] op_sel_hi:[1,0]
	v_pk_mul_f32 v[24:25], v[24:25], v[26:27]
	v_pk_mul_f32 v[22:23], v[22:23], v[28:29]
	v_pk_mul_f32 v[12:13], v[12:13], v[24:25]
	v_pk_mul_f32 v[14:15], v[14:15], v[22:23]
	ds_bpermute_b32 v20, v149, v20
	ds_bpermute_b32 v21, v149, v21
	v_cvt_pk_bf16_f32 v12, v12, v13
	v_cvt_pk_bf16_f32 v13, v14, v15
	ds_bpermute_b32 v12, v149, v12
	ds_bpermute_b32 v13, v149, v13
	v_add_u32_e32 v36, 0xa0, v151
	v_mad_i64_i32 v[14:15], s[22:23], v36, s47, v[136:137]
	v_lshl_add_u64 v[14:15], v[14:15], 0, v[140:141]
	s_waitcnt lgkmcnt(2)
	global_store_dwordx2 v[14:15], v[20:21], off
	s_waitcnt lgkmcnt(0)
	global_store_dwordx2 v[14:15], v[12:13], off offset:32
	v_pk_mul_f32 v[12:13], v[18:19], v[138:139] op_sel_hi:[1,0]
	v_pk_mul_f32 v[14:15], v[16:17], v[138:139] op_sel_hi:[1,0]
	v_mul_f32_e32 v18, 0xbfb8aa3b, v12
	v_mul_f32_e32 v16, 0xbfb8aa3b, v14
	v_mul_f32_e32 v17, 0xbfb8aa3b, v15
	v_mul_f32_e32 v19, 0xbfb8aa3b, v13
	v_exp_f32_e32 v16, v16
	v_exp_f32_e32 v17, v17
	v_exp_f32_e32 v18, v18
	v_exp_f32_e32 v19, v19
	v_add_f32_e32 v16, 1.0, v16
	v_add_f32_e32 v17, 1.0, v17
	v_add_f32_e32 v18, 1.0, v18
	v_add_f32_e32 v19, 1.0, v19
	v_rcp_f32_e32 v16, v16
	v_rcp_f32_e32 v17, v17
	v_rcp_f32_e32 v18, v18
	v_rcp_f32_e32 v19, v19
	v_pk_mul_f32 v[6:7], v[6:7], v[138:139] op_sel_hi:[1,0]
	v_pk_mul_f32 v[4:5], v[4:5], v[138:139] op_sel_hi:[1,0]
	v_pk_mul_f32 v[14:15], v[14:15], v[16:17]
	v_pk_mul_f32 v[12:13], v[12:13], v[18:19]
	v_pk_mul_f32 v[4:5], v[4:5], v[14:15]
	v_pk_mul_f32 v[6:7], v[6:7], v[12:13]
	v_cvt_pk_bf16_f32 v4, v4, v5
	v_cvt_pk_bf16_f32 v5, v6, v7
	v_pk_mul_f32 v[6:7], v[10:11], v[138:139] op_sel_hi:[1,0]
	v_pk_mul_f32 v[8:9], v[8:9], v[138:139] op_sel_hi:[1,0]
	v_mul_f32_e32 v12, 0xbfb8aa3b, v6
	v_mul_f32_e32 v10, 0xbfb8aa3b, v8
	v_mul_f32_e32 v11, 0xbfb8aa3b, v9
	v_mul_f32_e32 v13, 0xbfb8aa3b, v7
	v_exp_f32_e32 v10, v10
	v_exp_f32_e32 v11, v11
	v_exp_f32_e32 v12, v12
	v_exp_f32_e32 v13, v13
	v_add_f32_e32 v10, 1.0, v10
	v_add_f32_e32 v11, 1.0, v11
	v_add_f32_e32 v12, 1.0, v12
	v_add_f32_e32 v13, 1.0, v13
	v_rcp_f32_e32 v10, v10
	v_rcp_f32_e32 v11, v11
	v_rcp_f32_e32 v12, v12
	v_rcp_f32_e32 v13, v13
	v_pk_mul_f32 v[2:3], v[2:3], v[138:139] op_sel_hi:[1,0]
	v_pk_mul_f32 v[0:1], v[0:1], v[138:139] op_sel_hi:[1,0]
	v_pk_mul_f32 v[8:9], v[8:9], v[10:11]
	v_pk_mul_f32 v[6:7], v[6:7], v[12:13]
	v_pk_mul_f32 v[0:1], v[0:1], v[8:9]
	v_pk_mul_f32 v[2:3], v[2:3], v[6:7]
	ds_bpermute_b32 v4, v149, v4
	ds_bpermute_b32 v5, v149, v5
	v_cvt_pk_bf16_f32 v0, v0, v1
	v_cvt_pk_bf16_f32 v1, v2, v3
	ds_bpermute_b32 v0, v149, v0
	ds_bpermute_b32 v1, v149, v1
	v_add_u32_e32 v20, 0xb0, v151
	v_mad_i64_i32 v[2:3], s[22:23], v20, s47, v[136:137]
	v_lshl_add_u64 v[2:3], v[2:3], 0, v[140:141]
	s_mov_b64 s[22:23], s[16:17]
	s_waitcnt lgkmcnt(2)
	global_store_dwordx2 v[2:3], v[4:5], off
	s_waitcnt lgkmcnt(0)
	global_store_dwordx2 v[2:3], v[0:1], off offset:32
	s_cbranch_vccz .LBB0_1164
	s_waitcnt vmcnt(0)
	s_cmpk_gt_u32 s28, 0xff
	s_cbranch_scc1 .LBB0_1171
	s_barrier

.LBB0_1258:
	ds_read_b128 v[128:131], v159
	ds_read_b128 v[132:135], v159 offset:1024
	ds_read_b128 v[136:139], v159 offset:2048
	ds_read_b128 v[150:153], v159 offset:3072
	s_add_i32 s54, s18, 2
	s_add_u32 s19, s16, 0xffea0080
	s_addc_u32 s20, s17, -1
	s_cmp_eq_u32 s13, s18
	s_cselect_b32 s18, s4, s52
	s_cselect_b32 s21, s15, s20
	s_cselect_b32 s20, s14, s19
	s_cselect_b32 s19, s5, s53

	s_add_i32 m0, s26, 0xc000
	ds_read_b128 v[154:157], v160
	ds_read_b128 v[162:165], v160 offset:1024
	ds_read_b128 v[172:175], v160 offset:2048
	ds_read_b128 v[176:179], v160 offset:3072
	ds_read_b128 v[180:183], v160 offset:4096
	ds_read_b128 v[184:187], v160 offset:5120
	ds_read_b128 v[188:191], v160 offset:6144

	global_load_lds_dwordx4 v146, s[16:17]
	s_add_i32 m0, s26, 0xe000
	ds_read_b128 v[192:195], v160 offset:7168

	global_load_lds_dwordx4 v148, s[16:17]
	s_waitcnt lgkmcnt(8)
	s_barrier
	s_waitcnt lgkmcnt(0)


	v_mfma_f32_16x16x32_bf16 v[124:127], v[128:131], v[154:157], v[124:127]
	v_mfma_f32_16x16x32_bf16 v[120:123], v[136:139], v[154:157], v[120:123]
	v_mfma_f32_16x16x32_bf16 v[116:119], v[128:131], v[172:175], v[116:119]
	v_mfma_f32_16x16x32_bf16 v[104:107], v[136:139], v[172:175], v[104:107]
	v_mfma_f32_16x16x32_bf16 v[96:99], v[128:131], v[180:183], v[96:99]
	v_mfma_f32_16x16x32_bf16 v[88:91], v[136:139], v[180:183], v[88:91]
	v_mfma_f32_16x16x32_bf16 v[80:83], v[128:131], v[188:191], v[80:83]
	v_mfma_f32_16x16x32_bf16 v[72:75], v[136:139], v[188:191], v[72:75]
	v_mfma_f32_16x16x32_bf16 v[124:127], v[132:135], v[162:165], v[124:127]
	v_mfma_f32_16x16x32_bf16 v[120:123], v[150:153], v[162:165], v[120:123]
	v_mfma_f32_16x16x32_bf16 v[116:119], v[132:135], v[176:179], v[116:119]
	v_mfma_f32_16x16x32_bf16 v[104:107], v[150:153], v[176:179], v[104:107]
	v_mfma_f32_16x16x32_bf16 v[96:99], v[132:135], v[184:187], v[96:99]
	v_mfma_f32_16x16x32_bf16 v[88:91], v[150:153], v[184:187], v[88:91]
	v_mfma_f32_16x16x32_bf16 v[80:83], v[132:135], v[192:195], v[80:83]
	v_mfma_f32_16x16x32_bf16 v[72:75], v[150:153], v[192:195], v[72:75]

	s_barrier
	s_add_i32 s55, s35, s25
	s_add_u32 s66, s18, s6
	s_addc_u32 s67, s19, s7
	s_mov_b32 m0, s55
	ds_read_b128 v[196:199], v161
	ds_read_b128 v[200:203], v161 offset:1024
	ds_read_b128 v[204:207], v161 offset:2048

	global_load_lds_dwordx4 v140, s[18:19]
	s_add_i32 m0, s55, 0x2000
	ds_read_b128 v[212:215], v161 offset:3072

	global_load_lds_dwordx4 v142, s[18:19]
	s_barrier
	s_waitcnt lgkmcnt(0)


	v_mfma_f32_16x16x32_bf16 v[112:115], v[196:199], v[154:157], v[112:115]
	v_mfma_f32_16x16x32_bf16 v[108:111], v[204:207], v[154:157], v[108:111]
	v_mfma_f32_16x16x32_bf16 v[100:103], v[196:199], v[172:175], v[100:103]
	v_mfma_f32_16x16x32_bf16 v[92:95], v[204:207], v[172:175], v[92:95]
	v_mfma_f32_16x16x32_bf16 v[84:87], v[196:199], v[180:183], v[84:87]
	v_mfma_f32_16x16x32_bf16 v[76:79], v[204:207], v[180:183], v[76:79]
	v_mfma_f32_16x16x32_bf16 v[68:71], v[196:199], v[188:191], v[68:71]
	v_mfma_f32_16x16x32_bf16 v[64:67], v[204:207], v[188:191], v[64:67]
	v_mfma_f32_16x16x32_bf16 v[112:115], v[200:203], v[162:165], v[112:115]
	v_mfma_f32_16x16x32_bf16 v[108:111], v[212:215], v[162:165], v[108:111]
	v_mfma_f32_16x16x32_bf16 v[100:103], v[200:203], v[176:179], v[100:103]
	v_mfma_f32_16x16x32_bf16 v[92:95], v[212:215], v[176:179], v[92:95]
	v_mfma_f32_16x16x32_bf16 v[84:87], v[200:203], v[184:187], v[84:87]
	v_mfma_f32_16x16x32_bf16 v[76:79], v[212:215], v[184:187], v[76:79]
	v_mfma_f32_16x16x32_bf16 v[68:71], v[200:203], v[192:195], v[68:71]
	v_mfma_f32_16x16x32_bf16 v[64:67], v[212:215], v[192:195], v[64:67]

	s_mov_b32 m0, s26
	s_add_u32 s68, s20, s6
	s_addc_u32 s69, s21, s7
	s_barrier
	ds_read_b128 v[154:157], v160 offset:16384
	ds_read_b128 v[162:165], v160 offset:17408
	ds_read_b128 v[172:175], v160 offset:18432
	ds_read_b128 v[176:179], v160 offset:19456
	ds_read_b128 v[180:183], v160 offset:20480
	ds_read_b128 v[184:187], v160 offset:21504
	ds_read_b128 v[188:191], v160 offset:22528

	global_load_lds_dwordx4 v140, s[20:21]
	s_mov_b32 m0, s27
	ds_read_b128 v[192:195], v160 offset:23552

	global_load_lds_dwordx4 v142, s[20:21]
	s_barrier
	s_waitcnt lgkmcnt(0)


	v_mfma_f32_16x16x32_bf16 v[60:63], v[128:131], v[154:157], v[60:63]
	v_mfma_f32_16x16x32_bf16 v[56:59], v[136:139], v[154:157], v[56:59]
	v_mfma_f32_16x16x32_bf16 v[52:55], v[128:131], v[172:175], v[52:55]
	v_mfma_f32_16x16x32_bf16 v[40:43], v[136:139], v[172:175], v[40:43]
	v_mfma_f32_16x16x32_bf16 v[36:39], v[128:131], v[180:183], v[36:39]
	v_mfma_f32_16x16x32_bf16 v[24:27], v[136:139], v[180:183], v[24:27]
	v_mfma_f32_16x16x32_bf16 v[20:23], v[128:131], v[188:191], v[20:23]
	v_mfma_f32_16x16x32_bf16 v[8:11], v[136:139], v[188:191], v[8:11]
	v_mfma_f32_16x16x32_bf16 v[60:63], v[132:135], v[162:165], v[60:63]
	v_mfma_f32_16x16x32_bf16 v[56:59], v[150:153], v[162:165], v[56:59]
	v_mfma_f32_16x16x32_bf16 v[52:55], v[132:135], v[176:179], v[52:55]
	v_mfma_f32_16x16x32_bf16 v[40:43], v[150:153], v[176:179], v[40:43]
	v_mfma_f32_16x16x32_bf16 v[36:39], v[132:135], v[184:187], v[36:39]
	v_mfma_f32_16x16x32_bf16 v[24:27], v[150:153], v[184:187], v[24:27]
	v_mfma_f32_16x16x32_bf16 v[20:23], v[132:135], v[192:195], v[20:23]
	v_mfma_f32_16x16x32_bf16 v[8:11], v[150:153], v[192:195], v[8:11]

	s_barrier
	s_add_i32 s55, s36, s25
	s_mov_b32 m0, s55
	s_add_u32 s56, s18, 0x160000
	s_addc_u32 s57, s19, 0


	global_load_lds_dwordx4 v140, s[56:57]
	s_add_i32 m0, s55, 0x2000
	s_nop 0

	global_load_lds_dwordx4 v142, s[56:57]
	s_waitcnt vmcnt(6)
	s_barrier

	v_mfma_f32_16x16x32_bf16 v[48:51], v[196:199], v[154:157], v[48:51]
	v_mfma_f32_16x16x32_bf16 v[44:47], v[204:207], v[154:157], v[44:47]
	v_mfma_f32_16x16x32_bf16 v[32:35], v[196:199], v[172:175], v[32:35]
	v_mfma_f32_16x16x32_bf16 v[28:31], v[204:207], v[172:175], v[28:31]
	v_mfma_f32_16x16x32_bf16 v[16:19], v[196:199], v[180:183], v[16:19]
	v_mfma_f32_16x16x32_bf16 v[12:15], v[204:207], v[180:183], v[12:15]
	v_mfma_f32_16x16x32_bf16 v[4:7], v[196:199], v[188:191], v[4:7]
	v_mfma_f32_16x16x32_bf16 v[0:3], v[204:207], v[188:191], v[0:3]
	v_mfma_f32_16x16x32_bf16 v[48:51], v[200:203], v[162:165], v[48:51]
	v_mfma_f32_16x16x32_bf16 v[44:47], v[212:215], v[162:165], v[44:47]
	v_mfma_f32_16x16x32_bf16 v[32:35], v[200:203], v[176:179], v[32:35]
	v_mfma_f32_16x16x32_bf16 v[28:31], v[212:215], v[176:179], v[28:31]
	v_mfma_f32_16x16x32_bf16 v[16:19], v[200:203], v[184:187], v[16:19]
	v_mfma_f32_16x16x32_bf16 v[12:15], v[212:215], v[184:187], v[12:15]
	v_mfma_f32_16x16x32_bf16 v[4:7], v[200:203], v[192:195], v[4:7]
	v_mfma_f32_16x16x32_bf16 v[0:3], v[212:215], v[192:195], v[0:3]

	s_add_i32 s55, 0, 0x18000

	s_barrier
	ds_read_b128 v[128:131], v159 offset:32768
	ds_read_b128 v[132:135], v159 offset:33792
	ds_read_b128 v[136:139], v159 offset:34816
	ds_read_b128 v[150:153], v159 offset:35840
	s_add_u32 s20, s20, 0x160000
	s_addc_u32 s21, s21, 0
	s_mov_b32 m0, s28

	ds_read_b128 v[154:157], v160 offset:32768
	ds_read_b128 v[162:165], v160 offset:33792
	ds_read_b128 v[172:175], v160 offset:34816
	ds_read_b128 v[176:179], v160 offset:35840
	ds_read_b128 v[180:183], v160 offset:36864
	ds_read_b128 v[184:187], v160 offset:37888
	ds_read_b128 v[188:191], v160 offset:38912

	global_load_lds_dwordx4 v140, s[20:21]
	s_mov_b32 m0, s29
	ds_read_b128 v[192:195], v160 offset:39936

	global_load_lds_dwordx4 v142, s[20:21]
	s_waitcnt lgkmcnt(8)
	s_barrier
	s_waitcnt lgkmcnt(0)


	v_mfma_f32_16x16x32_bf16 v[124:127], v[128:131], v[154:157], v[124:127]
	v_mfma_f32_16x16x32_bf16 v[120:123], v[136:139], v[154:157], v[120:123]
	v_mfma_f32_16x16x32_bf16 v[116:119], v[128:131], v[172:175], v[116:119]
	v_mfma_f32_16x16x32_bf16 v[104:107], v[136:139], v[172:175], v[104:107]
	v_mfma_f32_16x16x32_bf16 v[96:99], v[128:131], v[180:183], v[96:99]
	v_mfma_f32_16x16x32_bf16 v[88:91], v[136:139], v[180:183], v[88:91]
	v_mfma_f32_16x16x32_bf16 v[80:83], v[128:131], v[188:191], v[80:83]
	v_mfma_f32_16x16x32_bf16 v[72:75], v[136:139], v[188:191], v[72:75]
	v_mfma_f32_16x16x32_bf16 v[124:127], v[132:135], v[162:165], v[124:127]
	v_mfma_f32_16x16x32_bf16 v[120:123], v[150:153], v[162:165], v[120:123]
	v_mfma_f32_16x16x32_bf16 v[116:119], v[132:135], v[176:179], v[116:119]
	v_mfma_f32_16x16x32_bf16 v[104:107], v[150:153], v[176:179], v[104:107]
	v_mfma_f32_16x16x32_bf16 v[96:99], v[132:135], v[184:187], v[96:99]
	v_mfma_f32_16x16x32_bf16 v[88:91], v[150:153], v[184:187], v[88:91]
	v_mfma_f32_16x16x32_bf16 v[80:83], v[132:135], v[192:195], v[80:83]
	v_mfma_f32_16x16x32_bf16 v[72:75], v[150:153], v[192:195], v[72:75]

	s_barrier
	s_add_i32 s20, 0, 0x1c000
	s_add_i32 s21, s55, s25


	s_mov_b32 m0, s21
	ds_read_b128 v[196:199], v161 offset:32768
	ds_read_b128 v[200:203], v161 offset:33792
	ds_read_b128 v[204:207], v161 offset:34816

	global_load_lds_dwordx4 v140, s[66:67]
	s_add_i32 m0, s21, 0x2000
	ds_read_b128 v[212:215], v161 offset:35840

	global_load_lds_dwordx4 v142, s[66:67]
	s_barrier
	s_waitcnt lgkmcnt(0)


	v_mfma_f32_16x16x32_bf16 v[112:115], v[196:199], v[154:157], v[112:115]
	v_mfma_f32_16x16x32_bf16 v[108:111], v[204:207], v[154:157], v[108:111]
	v_mfma_f32_16x16x32_bf16 v[100:103], v[196:199], v[172:175], v[100:103]
	v_mfma_f32_16x16x32_bf16 v[92:95], v[204:207], v[172:175], v[92:95]
	v_mfma_f32_16x16x32_bf16 v[84:87], v[196:199], v[180:183], v[84:87]
	v_mfma_f32_16x16x32_bf16 v[76:79], v[204:207], v[180:183], v[76:79]
	v_mfma_f32_16x16x32_bf16 v[68:71], v[196:199], v[188:191], v[68:71]
	v_mfma_f32_16x16x32_bf16 v[64:67], v[204:207], v[188:191], v[64:67]
	v_mfma_f32_16x16x32_bf16 v[112:115], v[200:203], v[162:165], v[112:115]
	v_mfma_f32_16x16x32_bf16 v[108:111], v[212:215], v[162:165], v[108:111]
	v_mfma_f32_16x16x32_bf16 v[100:103], v[200:203], v[176:179], v[100:103]
	v_mfma_f32_16x16x32_bf16 v[92:95], v[212:215], v[176:179], v[92:95]
	v_mfma_f32_16x16x32_bf16 v[84:87], v[200:203], v[184:187], v[84:87]
	v_mfma_f32_16x16x32_bf16 v[76:79], v[212:215], v[184:187], v[76:79]
	v_mfma_f32_16x16x32_bf16 v[68:71], v[200:203], v[192:195], v[68:71]
	v_mfma_f32_16x16x32_bf16 v[64:67], v[212:215], v[192:195], v[64:67]

	s_mov_b32 m0, s33

	s_barrier
	ds_read_b128 v[154:157], v160 offset:49152
	ds_read_b128 v[162:165], v160 offset:50176
	ds_read_b128 v[172:175], v160 offset:51200
	ds_read_b128 v[176:179], v160 offset:52224
	ds_read_b128 v[180:183], v160 offset:53248
	ds_read_b128 v[184:187], v160 offset:54272
	ds_read_b128 v[188:191], v160 offset:55296

	global_load_lds_dwordx4 v140, s[68:69]
	s_mov_b32 m0, s34
	ds_read_b128 v[192:195], v160 offset:56320

	global_load_lds_dwordx4 v142, s[68:69]
	s_barrier
	s_waitcnt lgkmcnt(0)


	v_mfma_f32_16x16x32_bf16 v[60:63], v[128:131], v[154:157], v[60:63]
	v_mfma_f32_16x16x32_bf16 v[56:59], v[136:139], v[154:157], v[56:59]
	v_mfma_f32_16x16x32_bf16 v[52:55], v[128:131], v[172:175], v[52:55]
	v_mfma_f32_16x16x32_bf16 v[40:43], v[136:139], v[172:175], v[40:43]
	v_mfma_f32_16x16x32_bf16 v[36:39], v[128:131], v[180:183], v[36:39]
	v_mfma_f32_16x16x32_bf16 v[24:27], v[136:139], v[180:183], v[24:27]
	v_mfma_f32_16x16x32_bf16 v[20:23], v[128:131], v[188:191], v[20:23]
	v_mfma_f32_16x16x32_bf16 v[8:11], v[136:139], v[188:191], v[8:11]
	v_mfma_f32_16x16x32_bf16 v[60:63], v[132:135], v[162:165], v[60:63]
	v_mfma_f32_16x16x32_bf16 v[56:59], v[150:153], v[162:165], v[56:59]
	v_mfma_f32_16x16x32_bf16 v[52:55], v[132:135], v[176:179], v[52:55]
	v_mfma_f32_16x16x32_bf16 v[40:43], v[150:153], v[176:179], v[40:43]
	v_mfma_f32_16x16x32_bf16 v[36:39], v[132:135], v[184:187], v[36:39]
	v_mfma_f32_16x16x32_bf16 v[24:27], v[150:153], v[184:187], v[24:27]
	v_mfma_f32_16x16x32_bf16 v[20:23], v[132:135], v[192:195], v[20:23]
	v_mfma_f32_16x16x32_bf16 v[8:11], v[150:153], v[192:195], v[8:11]

	s_barrier
	s_add_u32 s18, s18, 0x160080
	s_addc_u32 s19, s19, 0
	s_add_i32 s20, s20, s25
	s_mov_b32 m0, s20
	s_add_u32 s16, s16, 0x100
	s_addc_u32 s17, s17, 0

	global_load_lds_dwordx4 v140, s[18:19]
	s_add_i32 m0, s20, 0x2000
	s_add_u32 s52, s52, 0x100
	s_addc_u32 s53, s53, 0

	global_load_lds_dwordx4 v142, s[18:19]
	s_waitcnt vmcnt(6)
	s_barrier

	v_mfma_f32_16x16x32_bf16 v[48:51], v[196:199], v[154:157], v[48:51]
	v_mfma_f32_16x16x32_bf16 v[44:47], v[204:207], v[154:157], v[44:47]
	v_mfma_f32_16x16x32_bf16 v[32:35], v[196:199], v[172:175], v[32:35]
	v_mfma_f32_16x16x32_bf16 v[28:31], v[204:207], v[172:175], v[28:31]
	v_mfma_f32_16x16x32_bf16 v[16:19], v[196:199], v[180:183], v[16:19]
	v_mfma_f32_16x16x32_bf16 v[12:15], v[204:207], v[180:183], v[12:15]
	v_mfma_f32_16x16x32_bf16 v[4:7], v[196:199], v[188:191], v[4:7]
	v_mfma_f32_16x16x32_bf16 v[0:3], v[204:207], v[188:191], v[0:3]
	v_mfma_f32_16x16x32_bf16 v[48:51], v[200:203], v[162:165], v[48:51]
	v_mfma_f32_16x16x32_bf16 v[44:47], v[212:215], v[162:165], v[44:47]
	v_mfma_f32_16x16x32_bf16 v[32:35], v[200:203], v[176:179], v[32:35]
	v_mfma_f32_16x16x32_bf16 v[28:31], v[212:215], v[176:179], v[28:31]
	v_mfma_f32_16x16x32_bf16 v[16:19], v[200:203], v[184:187], v[16:19]
	v_mfma_f32_16x16x32_bf16 v[12:15], v[212:215], v[184:187], v[12:15]
	v_mfma_f32_16x16x32_bf16 v[4:7], v[200:203], v[192:195], v[4:7]
	v_mfma_f32_16x16x32_bf16 v[0:3], v[212:215], v[192:195], v[0:3]


	s_cmp_ge_i32 s54, s51
	s_mov_b32 s18, s54
	s_barrier
	s_cbranch_scc0 .LBB0_1258
	v_mov_b32_e32 v128, v210
	v_mov_b32_e32 v129, v169
	s_mov_b64 s[16:17], -1
	v_lshl_add_u32 v128, v128, 4, v129
	v_ashrrev_i32_e32 v150, 2, v128
	v_and_b32_e32 v129, 3, v129
	v_and_b32_e32 v128, -4, v128
	v_lshl_add_u32 v162, v129, 6, v128
	s_cmp_lt_i32 s2, 0
	v_lshlrev_b32_e32 v144, 4, v129
	s_cbranch_scc0 .LBB0_1261
	s_lshl_b32 s13, s50, 8
	s_add_i32 s13, s13, s30
	v_add_u32_e32 v128, s13, v150
	v_ashrrev_i32_e32 v129, 31, v128
	v_readlane_b32 s52, v254, 22
	v_lshlrev_b64 v[128:129], 13, v[128:129]
	v_readlane_b32 s66, v254, 36
	v_readlane_b32 s67, v254, 37
	s_lshl_b32 s16, s49, 8
	s_ashr_i32 s17, s16, 31
	v_lshl_add_u64 v[128:129], s[66:67], 0, v[128:129]
	v_lshl_add_u64 v[128:129], s[16:17], 2, v[128:129]
	s_lshl_b32 s16, s31, 2
	s_mov_b32 s17, s3
	v_lshl_add_u64 v[128:129], v[128:129], 0, s[16:17]
	v_lshl_add_u64 v[152:153], v[128:129], 0, v[144:145]
	global_load_dwordx4 v[164:167], v[152:153], off
	global_load_dwordx4 v[172:175], v[152:153], off offset:64
	global_load_dwordx4 v[176:179], v[152:153], off offset:512
	global_load_dwordx4 v[180:183], v[152:153], off offset:576
	v_add_co_u32_e32 v136, vcc, s37, v152
	ds_bpermute_b32 v138, v162, v124
	s_nop 0
	v_addc_co_u32_e32 v137, vcc, 0, v153, vcc
	global_load_dwordx4 v[184:187], v[136:137], off
	global_load_dwordx4 v[188:191], v[136:137], off offset:64
	global_load_dwordx4 v[192:195], v[136:137], off offset:512
	global_load_dwordx4 v[132:135], v[136:137], off offset:576
	v_add_co_u32_e32 v208, vcc, s38, v152
	ds_bpermute_b32 v139, v162, v125
	s_nop 0
	v_addc_co_u32_e32 v209, vcc, 0, v153, vcc
	global_load_dwordx4 v[196:199], v[208:209], off
	global_load_dwordx4 v[200:203], v[208:209], off offset:64
	global_load_dwordx4 v[204:207], v[208:209], off offset:512
	global_load_dwordx4 v[212:215], v[208:209], off offset:576
	v_add_co_u32_e32 v154, vcc, s39, v152
	ds_bpermute_b32 v156, v162, v126
	s_nop 0
	v_addc_co_u32_e32 v155, vcc, 0, v153, vcc
	global_load_dwordx4 v[216:219], v[154:155], off
	global_load_dwordx4 v[220:223], v[154:155], off offset:64
	global_load_dwordx4 v[224:227], v[154:155], off offset:512
	global_load_dwordx4 v[128:131], v[154:155], off offset:576
	ds_bpermute_b32 v157, v162, v127
	ds_bpermute_b32 v228, v162, v120
	ds_bpermute_b32 v229, v162, v121
	ds_bpermute_b32 v230, v162, v122
	ds_bpermute_b32 v231, v162, v123
	ds_bpermute_b32 v232, v162, v112
	ds_bpermute_b32 v233, v162, v113
	ds_bpermute_b32 v234, v162, v114
	ds_bpermute_b32 v235, v162, v115
	ds_bpermute_b32 v236, v162, v108
	ds_bpermute_b32 v237, v162, v109
	ds_bpermute_b32 v238, v162, v110
	ds_bpermute_b32 v239, v162, v111
	ds_bpermute_b32 v240, v162, v116
	ds_bpermute_b32 v241, v162, v117
	ds_bpermute_b32 v242, v162, v118
	ds_bpermute_b32 v243, v162, v119
	ds_bpermute_b32 v244, v162, v104
	ds_bpermute_b32 v245, v162, v105
	ds_bpermute_b32 v246, v162, v106
	ds_bpermute_b32 v247, v162, v107
	ds_bpermute_b32 v248, v162, v100
	ds_bpermute_b32 v249, v162, v101
	ds_bpermute_b32 v250, v162, v102
	ds_bpermute_b32 v251, v162, v103
	ds_bpermute_b32 v252, v162, v94
	ds_bpermute_b32 v253, v162, v95
	v_readlane_b32 s53, v254, 23
	v_readlane_b32 s54, v254, 24
	v_readlane_b32 s55, v254, 25
	v_readlane_b32 s56, v254, 26
	v_readlane_b32 s57, v254, 27
	v_readlane_b32 s58, v254, 28
	v_readlane_b32 s59, v254, 29
	v_readlane_b32 s60, v254, 30
	v_readlane_b32 s61, v254, 31
	v_readlane_b32 s62, v254, 32
	v_readlane_b32 s63, v254, 33
	v_readlane_b32 s64, v254, 34
	v_readlane_b32 s65, v254, 35
	s_mov_b64 s[16:17], 0
	s_waitcnt vmcnt(0) lgkmcnt(0)
	v_pk_add_f32 v[164:165], v[164:165], v[138:139]
	ds_bpermute_b32 v138, v162, v92
	ds_bpermute_b32 v139, v162, v93
	v_pk_add_f32 v[166:167], v[166:167], v[156:157]
	v_pk_add_f32 v[172:173], v[172:173], v[228:229]
	v_pk_add_f32 v[174:175], v[174:175], v[230:231]
	v_pk_add_f32 v[178:179], v[178:179], v[234:235]
	v_pk_add_f32 v[176:177], v[176:177], v[232:233]
	v_pk_add_f32 v[182:183], v[182:183], v[238:239]
	v_pk_add_f32 v[180:181], v[180:181], v[236:237]
	global_store_dwordx4 v[152:153], v[164:167], off
	global_store_dwordx4 v[152:153], v[172:175], off offset:64
	global_store_dwordx4 v[152:153], v[176:179], off offset:512
	global_store_dwordx4 v[152:153], v[180:183], off offset:576
	v_pk_add_f32 v[166:167], v[186:187], v[242:243]
	v_pk_add_f32 v[164:165], v[184:185], v[240:241]
	v_pk_add_f32 v[172:173], v[188:189], v[244:245]
	v_add_co_u32_e32 v156, vcc, s40, v152
	v_pk_add_f32 v[174:175], v[190:191], v[246:247]
	v_pk_add_f32 v[178:179], v[194:195], v[250:251]
	v_pk_add_f32 v[176:177], v[192:193], v[248:249]
	global_store_dwordx4 v[136:137], v[164:167], off
	global_store_dwordx4 v[136:137], v[172:175], off offset:64
	global_store_dwordx4 v[136:137], v[176:179], off offset:512
	v_addc_co_u32_e32 v157, vcc, 0, v153, vcc
	ds_bpermute_b32 v172, v162, v98
	ds_bpermute_b32 v173, v162, v99
	v_pk_add_f32 v[134:135], v[134:135], v[252:253]
	global_load_dwordx4 v[164:167], v[156:157], off
	s_waitcnt lgkmcnt(2)
	v_pk_add_f32 v[132:133], v[132:133], v[138:139]
	global_store_dwordx4 v[136:137], v[132:135], off offset:576
	ds_bpermute_b32 v132, v162, v96
	ds_bpermute_b32 v133, v162, v97
	ds_bpermute_b32 v136, v162, v90
	ds_bpermute_b32 v137, v162, v91
	ds_bpermute_b32 v138, v162, v88
	ds_bpermute_b32 v139, v162, v89
	s_waitcnt lgkmcnt(6)
	v_pk_add_f32 v[134:135], v[198:199], v[172:173]
	global_load_dwordx4 v[172:175], v[156:157], off offset:64
	s_waitcnt lgkmcnt(4)
	v_pk_add_f32 v[132:133], v[196:197], v[132:133]
	global_store_dwordx4 v[208:209], v[132:135], off
	ds_bpermute_b32 v180, v162, v76
	ds_bpermute_b32 v182, v162, v78
	s_waitcnt lgkmcnt(4)
	v_pk_add_f32 v[134:135], v[202:203], v[136:137]
	ds_bpermute_b32 v136, v162, v86
	ds_bpermute_b32 v137, v162, v87
	s_waitcnt lgkmcnt(4)
	v_pk_add_f32 v[132:133], v[200:201], v[138:139]
	ds_bpermute_b32 v138, v162, v84
	ds_bpermute_b32 v139, v162, v85
	global_store_dwordx4 v[208:209], v[132:135], off offset:64
	global_load_dwordx4 v[132:135], v[156:157], off offset:512
	s_waitcnt lgkmcnt(2)
	v_pk_add_f32 v[178:179], v[206:207], v[136:137]
	ds_bpermute_b32 v183, v162, v79
	s_waitcnt lgkmcnt(1)
	v_pk_add_f32 v[176:177], v[204:205], v[138:139]
	global_load_dwordx4 v[136:139], v[156:157], off offset:576
	ds_bpermute_b32 v181, v162, v77
	global_store_dwordx4 v[208:209], v[176:179], off offset:512
	v_add_co_u32_e32 v204, vcc, s41, v152
	s_waitcnt lgkmcnt(1)
	v_pk_add_f32 v[178:179], v[214:215], v[182:183]
	s_waitcnt lgkmcnt(0)
	v_pk_add_f32 v[176:177], v[212:213], v[180:181]
	ds_bpermute_b32 v180, v162, v80
	ds_bpermute_b32 v181, v162, v81
	ds_bpermute_b32 v182, v162, v82
	ds_bpermute_b32 v183, v162, v83
	v_addc_co_u32_e32 v205, vcc, 0, v153, vcc
	global_store_dwordx4 v[208:209], v[176:179], off offset:576
	global_load_dwordx4 v[176:179], v[204:205], off
	s_waitcnt lgkmcnt(0)
	v_pk_add_f32 v[182:183], v[218:219], v[182:183]
	global_load_dwordx4 v[184:187], v[204:205], off offset:64
	v_pk_add_f32 v[180:181], v[216:217], v[180:181]
	ds_bpermute_b32 v188, v162, v74
	ds_bpermute_b32 v189, v162, v75
	global_store_dwordx4 v[154:155], v[180:183], off
	ds_bpermute_b32 v180, v162, v72
	ds_bpermute_b32 v181, v162, v73
	ds_bpermute_b32 v192, v162, v68
	s_waitcnt lgkmcnt(3)
	v_pk_add_f32 v[182:183], v[222:223], v[188:189]
	global_load_dwordx4 v[188:191], v[204:205], off offset:512
	ds_bpermute_b32 v193, v162, v69
	s_waitcnt lgkmcnt(2)
	v_pk_add_f32 v[180:181], v[220:221], v[180:181]
	ds_bpermute_b32 v194, v162, v70
	ds_bpermute_b32 v195, v162, v71
	global_store_dwordx4 v[154:155], v[180:183], off offset:64
	global_load_dwordx4 v[180:183], v[204:205], off offset:576
	ds_bpermute_b32 v200, v162, v64
	ds_bpermute_b32 v196, v162, v66
	ds_bpermute_b32 v197, v162, v67
	ds_bpermute_b32 v201, v162, v65
	v_add_co_u32_e32 v206, vcc, s42, v152
	s_waitcnt lgkmcnt(4)
	v_pk_add_f32 v[194:195], v[226:227], v[194:195]
	v_pk_add_f32 v[192:193], v[224:225], v[192:193]
	v_addc_co_u32_e32 v207, vcc, 0, v153, vcc
	global_store_dwordx4 v[154:155], v[192:195], off offset:512
	global_load_dwordx4 v[192:195], v[206:207], off
	s_waitcnt lgkmcnt(1)
	v_pk_add_f32 v[130:131], v[130:131], v[196:197]
	s_waitcnt lgkmcnt(0)
	v_pk_add_f32 v[128:129], v[128:129], v[200:201]
	global_load_dwordx4 v[196:199], v[206:207], off offset:64
	ds_bpermute_b32 v202, v162, v62
	ds_bpermute_b32 v203, v162, v63
	global_store_dwordx4 v[154:155], v[128:131], off offset:576
	ds_bpermute_b32 v128, v162, v60
	ds_bpermute_b32 v129, v162, v61
	ds_bpermute_b32 v208, v162, v58
	ds_bpermute_b32 v209, v162, v59
	s_waitcnt vmcnt(18) lgkmcnt(4)
	v_pk_add_f32 v[130:131], v[166:167], v[202:203]
	ds_bpermute_b32 v154, v162, v56
	global_load_dwordx4 v[200:203], v[206:207], off offset:512
	ds_bpermute_b32 v155, v162, v57
	s_waitcnt lgkmcnt(4)
	v_pk_add_f32 v[128:129], v[164:165], v[128:129]
	global_load_dwordx4 v[164:167], v[206:207], off offset:576
	ds_bpermute_b32 v212, v162, v44
	global_store_dwordx4 v[156:157], v[128:131], off
	ds_bpermute_b32 v214, v162, v46
	ds_bpermute_b32 v215, v162, v47
	s_waitcnt vmcnt(19) lgkmcnt(5)
	v_pk_add_f32 v[130:131], v[174:175], v[208:209]
	v_add_co_u32_e32 v208, vcc, s43, v152
	s_waitcnt lgkmcnt(3)
	v_pk_add_f32 v[128:129], v[172:173], v[154:155]
	v_addc_co_u32_e32 v209, vcc, 0, v153, vcc
	global_store_dwordx4 v[156:157], v[128:131], off offset:64
	ds_bpermute_b32 v172, v162, v48
	ds_bpermute_b32 v173, v162, v49
	global_load_dwordx4 v[128:131], v[208:209], off
	global_load_dwordx4 v[152:155], v[208:209], off offset:64
	ds_bpermute_b32 v174, v162, v50
	ds_bpermute_b32 v175, v162, v51
	ds_bpermute_b32 v213, v162, v45
	s_waitcnt vmcnt(19) lgkmcnt(3)
	v_pk_add_f32 v[132:133], v[132:133], v[172:173]
	ds_bpermute_b32 v172, v162, v54
	ds_bpermute_b32 v173, v162, v55
	s_waitcnt lgkmcnt(3)
	v_pk_add_f32 v[134:135], v[134:135], v[174:175]
	global_store_dwordx4 v[156:157], v[132:135], off offset:512
	s_waitcnt vmcnt(16) lgkmcnt(0)
	v_pk_add_f32 v[174:175], v[178:179], v[172:173]
	v_pk_add_f32 v[134:135], v[138:139], v[214:215]
	v_pk_add_f32 v[132:133], v[136:137], v[212:213]
	global_store_dwordx4 v[156:157], v[132:135], off offset:576
	global_load_dwordx4 v[132:135], v[208:209], off offset:512
	ds_bpermute_b32 v156, v162, v52
	global_load_dwordx4 v[136:139], v[208:209], off offset:576
	ds_bpermute_b32 v157, v162, v53
	ds_bpermute_b32 v212, v162, v40
	ds_bpermute_b32 v214, v162, v42
	ds_bpermute_b32 v215, v162, v43
	ds_bpermute_b32 v213, v162, v41
	s_waitcnt lgkmcnt(4)
	v_pk_add_f32 v[172:173], v[176:177], v[156:157]
	global_store_dwordx4 v[204:205], v[172:175], off
	ds_bpermute_b32 v156, v162, v32
	ds_bpermute_b32 v157, v162, v33
	s_waitcnt vmcnt(19) lgkmcnt(3)
	v_pk_add_f32 v[174:175], v[186:187], v[214:215]
	s_waitcnt lgkmcnt(2)
	v_pk_add_f32 v[172:173], v[184:185], v[212:213]
	global_store_dwordx4 v[204:205], v[172:175], off offset:64
	ds_bpermute_b32 v172, v162, v34
	ds_bpermute_b32 v173, v162, v35
	ds_bpermute_b32 v176, v162, v28
	ds_bpermute_b32 v178, v162, v30
	ds_bpermute_b32 v179, v162, v31
	ds_bpermute_b32 v177, v162, v29
	s_waitcnt vmcnt(18) lgkmcnt(4)
	v_pk_add_f32 v[174:175], v[190:191], v[172:173]
	v_pk_add_f32 v[172:173], v[188:189], v[156:157]
	global_store_dwordx4 v[204:205], v[172:175], off offset:512
	ds_bpermute_b32 v156, v162, v36
	ds_bpermute_b32 v157, v162, v37
	s_waitcnt vmcnt(17) lgkmcnt(3)
	v_pk_add_f32 v[174:175], v[182:183], v[178:179]
	s_waitcnt lgkmcnt(2)
	v_pk_add_f32 v[172:173], v[180:181], v[176:177]
	global_store_dwordx4 v[204:205], v[172:175], off offset:576
	ds_bpermute_b32 v172, v162, v38
	ds_bpermute_b32 v173, v162, v39
	ds_bpermute_b32 v176, v162, v24
	ds_bpermute_b32 v178, v162, v26
	ds_bpermute_b32 v179, v162, v27
	ds_bpermute_b32 v177, v162, v25
	s_waitcnt vmcnt(16) lgkmcnt(4)
	v_pk_add_f32 v[174:175], v[194:195], v[172:173]
	v_pk_add_f32 v[172:173], v[192:193], v[156:157]
	global_store_dwordx4 v[206:207], v[172:175], off
	ds_bpermute_b32 v156, v162, v16
	ds_bpermute_b32 v157, v162, v17
	s_waitcnt vmcnt(16) lgkmcnt(3)
	v_pk_add_f32 v[174:175], v[198:199], v[178:179]
	s_waitcnt lgkmcnt(2)
	v_pk_add_f32 v[172:173], v[196:197], v[176:177]
	ds_bpermute_b32 v176, v162, v12
	ds_bpermute_b32 v178, v162, v14
	ds_bpermute_b32 v179, v162, v15
	ds_bpermute_b32 v177, v162, v13
	global_store_dwordx4 v[206:207], v[172:175], off offset:64
	ds_bpermute_b32 v172, v162, v18
	ds_bpermute_b32 v173, v162, v19
	s_waitcnt vmcnt(14) lgkmcnt(3)
	v_pk_add_f32 v[166:167], v[166:167], v[178:179]
	s_waitcnt lgkmcnt(2)
	v_pk_add_f32 v[164:165], v[164:165], v[176:177]
	global_store_dwordx4 v[206:207], v[164:167], off offset:576
	ds_bpermute_b32 v164, v162, v22
	s_waitcnt lgkmcnt(1)
	v_pk_add_f32 v[174:175], v[202:203], v[172:173]
	v_pk_add_f32 v[172:173], v[200:201], v[156:157]
	ds_bpermute_b32 v156, v162, v20
	ds_bpermute_b32 v157, v162, v21
	ds_bpermute_b32 v165, v162, v23
	global_store_dwordx4 v[206:207], v[172:175], off offset:512
	ds_bpermute_b32 v166, v162, v8
	ds_bpermute_b32 v172, v162, v10
	ds_bpermute_b32 v173, v162, v11
	ds_bpermute_b32 v167, v162, v9
	s_waitcnt vmcnt(13) lgkmcnt(4)
	v_pk_add_f32 v[130:131], v[130:131], v[164:165]
	v_pk_add_f32 v[128:129], v[128:129], v[156:157]
	global_store_dwordx4 v[208:209], v[128:131], off
	s_waitcnt vmcnt(13) lgkmcnt(1)
	s_nop 0
	v_pk_add_f32 v[130:131], v[154:155], v[172:173]
	s_waitcnt lgkmcnt(0)
	v_pk_add_f32 v[128:129], v[152:153], v[166:167]
	global_store_dwordx4 v[208:209], v[128:131], off offset:64
	ds_bpermute_b32 v128, v162, v4
	ds_bpermute_b32 v129, v162, v5
	ds_bpermute_b32 v130, v162, v6
	ds_bpermute_b32 v131, v162, v7
	ds_bpermute_b32 v152, v162, v0
	ds_bpermute_b32 v154, v162, v2
	ds_bpermute_b32 v155, v162, v3
	ds_bpermute_b32 v153, v162, v1
	s_waitcnt vmcnt(11) lgkmcnt(4)
	v_pk_add_f32 v[130:131], v[134:135], v[130:131]
	v_pk_add_f32 v[128:129], v[132:133], v[128:129]
	global_store_dwordx4 v[208:209], v[128:131], off offset:512
	s_waitcnt vmcnt(11) lgkmcnt(1)
	s_nop 0
	v_pk_add_f32 v[130:131], v[138:139], v[154:155]
	s_waitcnt lgkmcnt(0)
	v_pk_add_f32 v[128:129], v[136:137], v[152:153]
	global_store_dwordx4 v[208:209], v[128:131], off offset:576
